# mixerB HB loads hoisted + P3 epilogue loads deserialized + sample tail A preload
# speedup vs baseline: 1.0109x; 1.0109x over previous
.LBB0_194:
	s_cmpk_gt_i32 s86, 0xdf
	s_cselect_b64 s[8:9], -1, 0
	s_cmpk_lt_i32 s86, 0xe0
	s_cselect_b64 s[4:5], -1, 0
	s_cmpk_lt_i32 s2, 0xe0
	s_cselect_b64 s[0:1], -1, 0
	s_and_b64 s[6:7], s[0:1], s[8:9]
	s_andn2_b64 vcc, exec, s[6:7]
	s_cbranch_vccnz .LBB0_196
	v_and_b32_e32 v0, 0x7f, v201
	s_lshl_b32 s3, s2, 5
	s_lshl_b32 s6, s2, 4
	s_and_b32 s3, s3, 0xffffff00
	s_and_b32 s6, s6, 0x70
	v_lshlrev_b32_e32 v32, 4, v0
	v_mov_b32_e32 v33, 0
	s_waitcnt vmcnt(0)
	v_lshl_add_u32 v58, s90, 4, v233
	v_lshlrev_b32_e32 v58, 11, v58
	v_lshl_add_u32 v58, v232, 4, v58
	v_add_u32_e32 v58, 0x3500000, v58
	global_load_dwordx4 v[64:67], v58, s[68:69]
	global_load_dwordx4 v[68:71], v58, s[68:69] offset:64
	global_load_dwordx4 v[72:75], v58, s[68:69] offset:128
	global_load_dwordx4 v[76:79], v58, s[68:69] offset:192
	global_load_dwordx4 v[80:83], v58, s[68:69] offset:256
	global_load_dwordx4 v[84:87], v58, s[68:69] offset:320
	global_load_dwordx4 v[88:91], v58, s[68:69] offset:384
	global_load_dwordx4 v[92:95], v58, s[68:69] offset:448
	global_load_dwordx4 v[96:99], v58, s[68:69] offset:512
	global_load_dwordx4 v[100:103], v58, s[68:69] offset:576
	global_load_dwordx4 v[104:107], v58, s[68:69] offset:640
	global_load_dwordx4 v[108:111], v58, s[68:69] offset:704
	global_load_dwordx4 v[112:115], v58, s[68:69] offset:768
	global_load_dwordx4 v[116:119], v58, s[68:69] offset:832
	global_load_dwordx4 v[120:123], v58, s[68:69] offset:896
	global_load_dwordx4 v[124:127], v58, s[68:69] offset:960
	global_load_dwordx4 v[128:131], v58, s[68:69] offset:1024
	global_load_dwordx4 v[132:135], v58, s[68:69] offset:1088
	global_load_dwordx4 v[136:139], v58, s[68:69] offset:1152
	global_load_dwordx4 v[140:143], v58, s[68:69] offset:1216
	global_load_dwordx4 v[144:147], v58, s[68:69] offset:1280
	global_load_dwordx4 v[148:151], v58, s[68:69] offset:1344
	global_load_dwordx4 v[152:155], v58, s[68:69] offset:1408
	global_load_dwordx4 v[156:159], v58, s[68:69] offset:1472
	global_load_dwordx4 v[160:163], v58, s[68:69] offset:1536
	global_load_dwordx4 v[164:167], v58, s[68:69] offset:1600
	global_load_dwordx4 v[168:171], v58, s[68:69] offset:1664
	global_load_dwordx4 v[172:175], v58, s[68:69] offset:1728
	global_load_dwordx4 v[176:179], v58, s[68:69] offset:1792
	global_load_dwordx4 v[180:183], v58, s[68:69] offset:1856
	global_load_dwordx4 v[184:187], v58, s[68:69] offset:1920
	global_load_dwordx4 v[188:191], v58, s[68:69] offset:1984
	v_add_u32_e32 v28, 0xe00, v201
	s_or_b32 s3, s3, s6
	v_lshl_add_u64 v[24:25], s[84:85], 0, v[32:33]
	v_lshrrev_b32_e32 v33, 7, v201
	v_add_u32_e32 v35, 0x600, v201
	v_add_u32_e32 v18, 0xa00, v201
	v_lshrrev_b32_e32 v37, 7, v28
	v_lshrrev_b32_e32 v28, 4, v28
	v_or_b32_e32 v26, s3, v33
	v_add_u32_e32 v2, 0x200, v201
	v_lshrrev_b32_e32 v10, 4, v35
	v_lshrrev_b32_e32 v36, 7, v18
	v_and_b32_e32 v28, 0x180, v28
	v_ashrrev_i32_e32 v27, 31, v26
	v_lshrrev_b32_e32 v34, 7, v2
	v_and_b32_e32 v10, 0x80, v10
	v_bfe_u32 v11, v35, 7, 4
	v_and_or_b32 v18, v36, 15, s3
	v_add_u32_e32 v28, s3, v28
	v_lshlrev_b64 v[0:1], 11, v[26:27]
	v_or_b32_e32 v2, s3, v34
	v_or_b32_e32 v8, 8, v26
	v_or3_b32 v10, v10, v11, s3
	v_or_b32_e32 v16, 0x80, v26
	v_or_b32_e32 v18, 0x80, v18
	v_or_b32_e32 v26, 0x88, v26
	v_and_or_b32 v28, v37, 15, v28
	v_ashrrev_i32_e32 v3, 31, v2
	v_ashrrev_i32_e32 v9, 31, v8
	v_ashrrev_i32_e32 v11, 31, v10
	v_ashrrev_i32_e32 v17, 31, v16
	v_ashrrev_i32_e32 v19, 31, v18
	v_ashrrev_i32_e32 v27, 31, v26
	v_ashrrev_i32_e32 v29, 31, v28
	v_lshlrev_b64 v[2:3], 11, v[2:3]
	v_lshlrev_b64 v[8:9], 11, v[8:9]
	v_lshlrev_b64 v[10:11], 11, v[10:11]
	v_lshlrev_b64 v[16:17], 11, v[16:17]
	v_lshlrev_b64 v[18:19], 11, v[18:19]
	v_lshlrev_b64 v[26:27], 11, v[26:27]
	v_lshlrev_b64 v[28:29], 11, v[28:29]
	v_lshl_add_u64 v[0:1], v[24:25], 0, v[0:1]
	v_lshl_add_u64 v[4:5], v[24:25], 0, v[2:3]
	v_lshl_add_u64 v[8:9], v[24:25], 0, v[8:9]
	v_lshl_add_u64 v[12:13], v[24:25], 0, v[10:11]
	v_lshl_add_u64 v[16:17], v[24:25], 0, v[16:17]
	v_lshl_add_u64 v[20:21], v[24:25], 0, v[18:19]
	v_lshl_add_u64 v[26:27], v[24:25], 0, v[26:27]
	v_lshl_add_u64 v[28:29], v[24:25], 0, v[28:29]
	global_load_dwordx4 v[0:3], v[0:1], off
	s_nop 0
	global_load_dwordx4 v[4:7], v[4:5], off
	s_nop 0
	global_load_dwordx4 v[8:11], v[8:9], off
	s_nop 0
	global_load_dwordx4 v[12:15], v[12:13], off
	s_nop 0
	global_load_dwordx4 v[16:19], v[16:17], off
	s_nop 0
	global_load_dwordx4 v[20:23], v[20:21], off
	s_nop 0
	global_load_dwordx4 v[24:27], v[26:27], off
	s_nop 0
	global_load_dwordx4 v[28:31], v[28:29], off
	s_movk_i32 s3, 0x810
	v_add_u32_e32 v32, 0, v32
	v_lshrrev_b32_e32 v35, 7, v35
	v_mad_u32_u24 v33, v33, s3, v32
	v_mad_u32_u24 v34, v34, s3, v32
	v_mad_u32_u24 v35, v35, s3, v32
	v_mad_u32_u24 v36, v36, s3, v32
	v_mad_u32_u24 v32, v37, s3, v32
	s_waitcnt vmcnt(7)
	ds_write_b128 v33, v[0:3]
	s_waitcnt vmcnt(6)
	ds_write_b128 v34, v[4:7]
	s_waitcnt vmcnt(5)
	ds_write_b128 v33, v[8:11] offset:16512
	s_waitcnt vmcnt(4)
	ds_write_b128 v35, v[12:15]
	s_waitcnt vmcnt(3)
	ds_write_b128 v33, v[16:19] offset:33024
	s_waitcnt vmcnt(2)
	ds_write_b128 v36, v[20:23]
	s_waitcnt vmcnt(1)
	ds_write_b128 v33, v[24:27] offset:49536
	s_waitcnt vmcnt(0)
	ds_write_b128 v32, v[28:31]
	s_waitcnt lgkmcnt(0)
	s_barrier

.LBB0_210:
	s_waitcnt vmcnt(0)
	ds_read_b128 v[22:25], v10
	ds_read_b128 v[26:29], v10 offset:33024
	ds_read_b128 v[30:33], v10 offset:64
	ds_read_b128 v[34:37], v10 offset:33088
	s_waitcnt lgkmcnt(2)
	v_mfma_f32_16x16x32_bf16 v[4:7], v[22:25], v[64:67], v[4:7]
	v_mfma_f32_16x16x32_bf16 v[0:3], v[26:29], v[64:67], v[0:3]
	ds_read_b128 v[22:25], v10 offset:128
	ds_read_b128 v[26:29], v10 offset:33152
	s_waitcnt lgkmcnt(2)
	v_mfma_f32_16x16x32_bf16 v[4:7], v[30:33], v[68:71], v[4:7]
	v_mfma_f32_16x16x32_bf16 v[0:3], v[34:37], v[68:71], v[0:3]
	ds_read_b128 v[30:33], v10 offset:192
	ds_read_b128 v[34:37], v10 offset:33216
	s_waitcnt lgkmcnt(2)
	v_mfma_f32_16x16x32_bf16 v[4:7], v[22:25], v[72:75], v[4:7]
	v_mfma_f32_16x16x32_bf16 v[0:3], v[26:29], v[72:75], v[0:3]
	ds_read_b128 v[22:25], v10 offset:256
	ds_read_b128 v[26:29], v10 offset:33280
	s_waitcnt lgkmcnt(2)
	v_mfma_f32_16x16x32_bf16 v[4:7], v[30:33], v[76:79], v[4:7]
	v_mfma_f32_16x16x32_bf16 v[0:3], v[34:37], v[76:79], v[0:3]
	ds_read_b128 v[30:33], v10 offset:320
	ds_read_b128 v[34:37], v10 offset:33344
	s_waitcnt lgkmcnt(2)
	v_mfma_f32_16x16x32_bf16 v[4:7], v[22:25], v[80:83], v[4:7]
	v_mfma_f32_16x16x32_bf16 v[0:3], v[26:29], v[80:83], v[0:3]
	ds_read_b128 v[22:25], v10 offset:384
	ds_read_b128 v[26:29], v10 offset:33408
	s_waitcnt lgkmcnt(2)
	v_mfma_f32_16x16x32_bf16 v[4:7], v[30:33], v[84:87], v[4:7]
	v_mfma_f32_16x16x32_bf16 v[0:3], v[34:37], v[84:87], v[0:3]
	ds_read_b128 v[30:33], v10 offset:448
	ds_read_b128 v[34:37], v10 offset:33472
	s_waitcnt lgkmcnt(2)
	v_mfma_f32_16x16x32_bf16 v[4:7], v[22:25], v[88:91], v[4:7]
	v_mfma_f32_16x16x32_bf16 v[0:3], v[26:29], v[88:91], v[0:3]
	ds_read_b128 v[22:25], v10 offset:512
	ds_read_b128 v[26:29], v10 offset:33536
	s_waitcnt lgkmcnt(2)
	v_mfma_f32_16x16x32_bf16 v[4:7], v[30:33], v[92:95], v[4:7]
	v_mfma_f32_16x16x32_bf16 v[0:3], v[34:37], v[92:95], v[0:3]
	ds_read_b128 v[30:33], v10 offset:576
	ds_read_b128 v[34:37], v10 offset:33600
	s_waitcnt lgkmcnt(2)
	v_mfma_f32_16x16x32_bf16 v[4:7], v[22:25], v[96:99], v[4:7]
	v_mfma_f32_16x16x32_bf16 v[0:3], v[26:29], v[96:99], v[0:3]
	ds_read_b128 v[22:25], v10 offset:640
	ds_read_b128 v[26:29], v10 offset:33664
	s_waitcnt lgkmcnt(2)
	v_mfma_f32_16x16x32_bf16 v[4:7], v[30:33], v[100:103], v[4:7]
	v_mfma_f32_16x16x32_bf16 v[0:3], v[34:37], v[100:103], v[0:3]
	ds_read_b128 v[30:33], v10 offset:704
	ds_read_b128 v[34:37], v10 offset:33728
	s_waitcnt lgkmcnt(2)
	v_mfma_f32_16x16x32_bf16 v[4:7], v[22:25], v[104:107], v[4:7]
	v_mfma_f32_16x16x32_bf16 v[0:3], v[26:29], v[104:107], v[0:3]
	ds_read_b128 v[22:25], v10 offset:768
	ds_read_b128 v[26:29], v10 offset:33792
	s_waitcnt lgkmcnt(2)
	v_mfma_f32_16x16x32_bf16 v[4:7], v[30:33], v[108:111], v[4:7]
	v_mfma_f32_16x16x32_bf16 v[0:3], v[34:37], v[108:111], v[0:3]
	ds_read_b128 v[30:33], v10 offset:832
	ds_read_b128 v[34:37], v10 offset:33856
	s_waitcnt lgkmcnt(2)
	v_mfma_f32_16x16x32_bf16 v[4:7], v[22:25], v[112:115], v[4:7]
	v_mfma_f32_16x16x32_bf16 v[0:3], v[26:29], v[112:115], v[0:3]
	ds_read_b128 v[22:25], v10 offset:896
	ds_read_b128 v[26:29], v10 offset:33920
	s_waitcnt lgkmcnt(2)
	v_mfma_f32_16x16x32_bf16 v[4:7], v[30:33], v[116:119], v[4:7]
	v_mfma_f32_16x16x32_bf16 v[0:3], v[34:37], v[116:119], v[0:3]
	ds_read_b128 v[30:33], v10 offset:960
	ds_read_b128 v[34:37], v10 offset:33984
	s_waitcnt lgkmcnt(2)
	v_mfma_f32_16x16x32_bf16 v[4:7], v[22:25], v[120:123], v[4:7]
	v_mfma_f32_16x16x32_bf16 v[0:3], v[26:29], v[120:123], v[0:3]
	ds_read_b128 v[22:25], v10 offset:1024
	ds_read_b128 v[26:29], v10 offset:34048
	s_waitcnt lgkmcnt(2)
	v_mfma_f32_16x16x32_bf16 v[4:7], v[30:33], v[124:127], v[4:7]
	v_mfma_f32_16x16x32_bf16 v[0:3], v[34:37], v[124:127], v[0:3]
	ds_read_b128 v[30:33], v10 offset:1088
	ds_read_b128 v[34:37], v10 offset:34112
	s_waitcnt lgkmcnt(2)
	v_mfma_f32_16x16x32_bf16 v[4:7], v[22:25], v[128:131], v[4:7]
	v_mfma_f32_16x16x32_bf16 v[0:3], v[26:29], v[128:131], v[0:3]
	ds_read_b128 v[22:25], v10 offset:1152
	ds_read_b128 v[26:29], v10 offset:34176
	s_waitcnt lgkmcnt(2)
	v_mfma_f32_16x16x32_bf16 v[4:7], v[30:33], v[132:135], v[4:7]
	v_mfma_f32_16x16x32_bf16 v[0:3], v[34:37], v[132:135], v[0:3]
	ds_read_b128 v[30:33], v10 offset:1216
	ds_read_b128 v[34:37], v10 offset:34240
	s_waitcnt lgkmcnt(2)
	v_mfma_f32_16x16x32_bf16 v[4:7], v[22:25], v[136:139], v[4:7]
	v_mfma_f32_16x16x32_bf16 v[0:3], v[26:29], v[136:139], v[0:3]
	ds_read_b128 v[22:25], v10 offset:1280
	ds_read_b128 v[26:29], v10 offset:34304
	s_waitcnt lgkmcnt(2)
	v_mfma_f32_16x16x32_bf16 v[4:7], v[30:33], v[140:143], v[4:7]
	v_mfma_f32_16x16x32_bf16 v[0:3], v[34:37], v[140:143], v[0:3]
	ds_read_b128 v[30:33], v10 offset:1344
	ds_read_b128 v[34:37], v10 offset:34368
	s_waitcnt lgkmcnt(2)
	v_mfma_f32_16x16x32_bf16 v[4:7], v[22:25], v[144:147], v[4:7]
	v_mfma_f32_16x16x32_bf16 v[0:3], v[26:29], v[144:147], v[0:3]
	ds_read_b128 v[22:25], v10 offset:1408
	ds_read_b128 v[26:29], v10 offset:34432
	s_waitcnt lgkmcnt(2)
	v_mfma_f32_16x16x32_bf16 v[4:7], v[30:33], v[148:151], v[4:7]
	v_mfma_f32_16x16x32_bf16 v[0:3], v[34:37], v[148:151], v[0:3]
	ds_read_b128 v[30:33], v10 offset:1472
	ds_read_b128 v[34:37], v10 offset:34496
	s_waitcnt lgkmcnt(2)
	v_mfma_f32_16x16x32_bf16 v[4:7], v[22:25], v[152:155], v[4:7]
	v_mfma_f32_16x16x32_bf16 v[0:3], v[26:29], v[152:155], v[0:3]
	ds_read_b128 v[22:25], v10 offset:1536
	ds_read_b128 v[26:29], v10 offset:34560
	s_waitcnt lgkmcnt(2)
	v_mfma_f32_16x16x32_bf16 v[4:7], v[30:33], v[156:159], v[4:7]
	v_mfma_f32_16x16x32_bf16 v[0:3], v[34:37], v[156:159], v[0:3]
	ds_read_b128 v[30:33], v10 offset:1600
	ds_read_b128 v[34:37], v10 offset:34624
	s_waitcnt lgkmcnt(2)
	v_mfma_f32_16x16x32_bf16 v[4:7], v[22:25], v[160:163], v[4:7]
	v_mfma_f32_16x16x32_bf16 v[0:3], v[26:29], v[160:163], v[0:3]
	ds_read_b128 v[22:25], v10 offset:1664
	ds_read_b128 v[26:29], v10 offset:34688
	s_waitcnt lgkmcnt(2)
	v_mfma_f32_16x16x32_bf16 v[4:7], v[30:33], v[164:167], v[4:7]
	v_mfma_f32_16x16x32_bf16 v[0:3], v[34:37], v[164:167], v[0:3]
	ds_read_b128 v[30:33], v10 offset:1728
	ds_read_b128 v[34:37], v10 offset:34752
	s_waitcnt lgkmcnt(2)
	v_mfma_f32_16x16x32_bf16 v[4:7], v[22:25], v[168:171], v[4:7]
	v_mfma_f32_16x16x32_bf16 v[0:3], v[26:29], v[168:171], v[0:3]
	ds_read_b128 v[22:25], v10 offset:1792
	ds_read_b128 v[26:29], v10 offset:34816
	s_waitcnt lgkmcnt(2)
	v_mfma_f32_16x16x32_bf16 v[4:7], v[30:33], v[172:175], v[4:7]
	v_mfma_f32_16x16x32_bf16 v[0:3], v[34:37], v[172:175], v[0:3]
	ds_read_b128 v[30:33], v10 offset:1856
	ds_read_b128 v[34:37], v10 offset:34880
	s_waitcnt lgkmcnt(2)
	v_mfma_f32_16x16x32_bf16 v[4:7], v[22:25], v[176:179], v[4:7]
	v_mfma_f32_16x16x32_bf16 v[0:3], v[26:29], v[176:179], v[0:3]
	ds_read_b128 v[22:25], v10 offset:1920
	ds_read_b128 v[26:29], v10 offset:34944
	s_waitcnt lgkmcnt(2)
	v_mfma_f32_16x16x32_bf16 v[4:7], v[30:33], v[180:183], v[4:7]
	v_mfma_f32_16x16x32_bf16 v[0:3], v[34:37], v[180:183], v[0:3]
	ds_read_b128 v[30:33], v10 offset:1984
	ds_read_b128 v[34:37], v10 offset:35008
	s_waitcnt lgkmcnt(2)
	v_mfma_f32_16x16x32_bf16 v[4:7], v[22:25], v[184:187], v[4:7]
	v_mfma_f32_16x16x32_bf16 v[0:3], v[26:29], v[184:187], v[0:3]
	s_waitcnt lgkmcnt(0)
	v_mfma_f32_16x16x32_bf16 v[4:7], v[30:33], v[188:191], v[4:7]
	v_mfma_f32_16x16x32_bf16 v[0:3], v[34:37], v[188:191], v[0:3]
	s_lshl_b32 s21, s19, 4

.LBB0_314:
	s_or_b64 exec, exec, s[40:41]
	v_or_b32_e32 v187, s11, v233
	v_lshlrev_b32_e32 v187, 11, v187
	v_lshl_add_u32 v187, v210, 1, v187
	v_mov_b32_e32 v250, 0
	v_mov_b32_e32 v251, 0
	v_mov_b32_e32 v252, 0
	v_mov_b32_e32 v253, 0
	s_mov_b64 s[40:41], exec
	s_and_b64 exec, exec, s[8:9]
	v_add_u32_e32 v255, 0x38000, v187
	s_nop 0
	global_load_dwordx4 v[250:253], v255, s[50:51]
	s_mov_b64 exec, s[40:41]
	global_load_dwordx4 v[188:191], v187, s[50:51]
	v_add_u32_e32 v255, 0x8000, v187
	global_load_dwordx4 v[192:195], v255, s[50:51]
	v_add_u32_e32 v255, 0x10000, v187
	global_load_dwordx4 v[196:199], v255, s[50:51]
	v_add_u32_e32 v255, 0x18000, v187
	global_load_dwordx4 v[228:231], v255, s[50:51]
	v_add_u32_e32 v255, 0x40000, v187
	global_load_dwordx4 v[246:249], v255, s[50:51]
	v_mul_f32_e32 v144, 0xbfb8aa3b, v128
	v_mul_f32_e32 v145, 0xbfb8aa3b, v129
	v_exp_f32_e32 v144, v144
	v_exp_f32_e32 v145, v145
	v_mul_f32_e32 v146, 0xbfb8aa3b, v130
	v_mul_f32_e32 v147, 0xbfb8aa3b, v131
	v_exp_f32_e32 v146, v146
	v_exp_f32_e32 v147, v147
	v_add_f32_e32 v144, 1.0, v144
	v_add_f32_e32 v145, 1.0, v145
	v_rcp_f32_e32 v144, v144
	v_rcp_f32_e32 v145, v145
	v_add_f32_e32 v146, 1.0, v146
	v_add_f32_e32 v147, 1.0, v147
	v_rcp_f32_e32 v146, v146
	v_rcp_f32_e32 v147, v147
	v_pk_mul_f32 v[164:165], v[128:129], v[144:145]
	v_mul_f32_e32 v144, 0xbfb8aa3b, v120
	v_mul_f32_e32 v145, 0xbfb8aa3b, v121
	v_exp_f32_e32 v144, v144
	v_exp_f32_e32 v145, v145
	v_pk_mul_f32 v[166:167], v[130:131], v[146:147]
	v_mul_f32_e32 v146, 0xbfb8aa3b, v122
	v_mul_f32_e32 v147, 0xbfb8aa3b, v123
	v_exp_f32_e32 v146, v146
	v_exp_f32_e32 v147, v147
	v_add_f32_e32 v144, 1.0, v144
	v_add_f32_e32 v145, 1.0, v145
	v_rcp_f32_e32 v144, v144
	v_rcp_f32_e32 v145, v145
	v_or_b32_e32 v162, s11, v233
	v_add_f32_e32 v146, 1.0, v146
	v_add_f32_e32 v147, 1.0, v147
	v_rcp_f32_e32 v146, v146
	v_rcp_f32_e32 v147, v147
	v_ashrrev_i32_e32 v163, 31, v162
	v_pk_mul_f32 v[170:171], v[120:121], v[144:145]
	v_lshlrev_b64 v[144:145], 11, v[162:163]
	v_lshl_add_u64 v[144:145], s[50:51], 0, v[144:145]
	v_lshlrev_b64 v[160:161], 1, v[210:211]
	v_lshl_add_u64 v[144:145], v[144:145], 0, v[160:161]
	v_pk_mul_f32 v[168:169], v[122:123], v[146:147]
	s_waitcnt vmcnt(4)
	v_mov_b32_e32 v144, v188
	v_mov_b32_e32 v145, v189
	v_mov_b32_e32 v146, v190
	v_mov_b32_e32 v147, v191
	v_add_u32_e32 v255, 0x48000, v187
	global_load_dwordx4 v[188:191], v255, s[50:51]
	v_mov_b32_e32 v173, v211
	v_mov_b32_e32 v174, v211
	v_mov_b32_e32 v175, v211
	v_mov_b32_e32 v176, v211
	v_mov_b32_e32 v177, v211
	v_mov_b32_e32 v178, v211
	v_mov_b32_e32 v179, v211
	v_pk_mul_f32 v[170:171], v[124:125], v[170:171]
	v_pk_mul_f32 v[168:169], v[126:127], v[168:169]
	v_mov_b32_e32 v184, v211
	v_mov_b32_e32 v185, v211
	s_movk_i32 s16, 0x7ff
	v_cndmask_b32_e64 v172, v144, v156, s[4:5]
	v_cndmask_b32_e64 v156, v156, v144, s[0:1]
	s_nop 0
	v_mov_b32_dpp v173, v172 row_ror:1 row_mask:0xf bank_mask:0xf
	v_mov_b32_e32 v172, v211
	s_nop 1
	v_mov_b32_dpp v172, v156 row_ror:2 row_mask:0xf bank_mask:0xf
	v_cndmask_b32_e64 v156, v145, v157, s[4:5]
	v_cndmask_b32_e64 v157, v157, v145, s[0:1]
	v_lshlrev_b32_e32 v180, 16, v172
	v_mov_b32_dpp v174, v156 row_ror:1 row_mask:0xf bank_mask:0xf
	v_mov_b32_dpp v175, v157 row_ror:2 row_mask:0xf bank_mask:0xf
	v_cndmask_b32_e64 v156, v146, v158, s[4:5]
	v_cndmask_b32_e64 v157, v158, v146, s[0:1]
	v_lshlrev_b32_e32 v158, 16, v144
	v_mov_b32_dpp v176, v156 row_ror:1 row_mask:0xf bank_mask:0xf
	v_mov_b32_dpp v177, v157 row_ror:2 row_mask:0xf bank_mask:0xf
	v_cndmask_b32_e64 v156, v147, v159, s[4:5]
	v_cndmask_b32_e64 v157, v159, v147, s[0:1]
	v_lshlrev_b32_e32 v159, 16, v173
	v_mov_b32_dpp v178, v156 row_ror:1 row_mask:0xf bank_mask:0xf
	v_mov_b32_dpp v179, v157 row_ror:2 row_mask:0xf bank_mask:0xf
	v_mov_b32_e32 v156, v152
	v_mov_b32_e32 v157, v140
	v_pk_mul_f32 v[158:159], v[156:157], v[158:159]
	v_and_b32_e32 v172, 0xffff0000, v172
	v_fma_f32 v140, v136, v180, v159
	v_add_f32_e32 v180, v158, v140
	v_and_b32_e32 v159, 0xffff0000, v173
	v_and_b32_e32 v158, 0xffff0000, v144
	v_mov_b32_e32 v140, v153
	v_pk_mul_f32 v[152:153], v[140:141], v[158:159]
	v_lshlrev_b32_e32 v158, 16, v145
	v_fma_f32 v153, v137, v172, v153
	v_add_f32_e32 v172, v152, v153
	v_lshlrev_b32_e32 v159, 16, v174
	v_mov_b32_e32 v152, v154
	v_mov_b32_e32 v153, v142
	v_lshlrev_b32_e32 v173, 16, v175
	v_pk_mul_f32 v[158:159], v[152:153], v[158:159]
	v_and_b32_e32 v175, 0xffff0000, v175
	v_fma_f32 v142, v138, v173, v159
	v_add_f32_e32 v173, v158, v142
	v_and_b32_e32 v159, 0xffff0000, v174
	v_and_b32_e32 v158, 0xffff0000, v145
	v_mov_b32_e32 v142, v155
	v_pk_mul_f32 v[154:155], v[142:143], v[158:159]
	v_lshlrev_b32_e32 v158, 16, v146
	v_fma_f32 v155, v139, v175, v155
	v_add_f32_e32 v174, v154, v155
	v_lshlrev_b32_e32 v159, 16, v176
	v_mov_b32_e32 v154, v148
	v_mov_b32_e32 v155, v116
	v_lshlrev_b32_e32 v175, 16, v177
	v_pk_mul_f32 v[158:159], v[154:155], v[158:159]
	v_and_b32_e32 v177, 0xffff0000, v177
	v_fma_f32 v116, v112, v175, v159
	v_add_f32_e32 v175, v158, v116
	v_and_b32_e32 v159, 0xffff0000, v176
	v_and_b32_e32 v158, 0xffff0000, v146
	v_mov_b32_e32 v116, v149
	v_pk_mul_f32 v[148:149], v[116:117], v[158:159]
	v_mov_b32_e32 v158, v150
	v_fma_f32 v149, v113, v177, v149
	v_add_f32_e32 v176, v148, v149
	v_lshlrev_b32_e32 v148, 16, v147
	v_lshlrev_b32_e32 v149, 16, v178
	v_mov_b32_e32 v159, v118
	v_lshlrev_b32_e32 v177, 16, v179
	v_pk_mul_f32 v[148:149], v[158:159], v[148:149]
	v_and_b32_e32 v150, 0xffff0000, v179
	v_fma_f32 v118, v114, v177, v149
	v_add_f32_e32 v177, v148, v118
	v_and_b32_e32 v149, 0xffff0000, v178
	v_and_b32_e32 v148, 0xffff0000, v147
	v_mov_b32_e32 v118, v151
	v_pk_mul_f32 v[148:149], v[118:119], v[148:149]
	v_mov_b32_e32 v179, v211
	v_fma_f32 v149, v115, v150, v149
	v_add_f32_e32 v178, v148, v149
	v_pk_mul_f32 v[148:149], v[132:133], v[164:165]
	v_pk_mul_f32 v[150:151], v[134:135], v[166:167]
	v_mul_f32_e32 v148, v148, v180
	v_mul_f32_e32 v149, v149, v172
	v_cvt_pk_bf16_f32 v148, v148, v149
	v_mul_f32_e32 v149, v150, v173
	v_mul_f32_e32 v150, v151, v174
	v_cvt_pk_bf16_f32 v149, v149, v150
	v_mul_f32_e32 v150, v170, v175
	v_mul_f32_e32 v151, v171, v176
	v_cvt_pk_bf16_f32 v150, v150, v151
	v_mul_f32_e32 v151, v168, v177
	v_mul_f32_e32 v164, v169, v178
	v_cvt_pk_bf16_f32 v151, v151, v164
	v_lshlrev_b64 v[164:165], 12, v[162:163]
	v_lshl_add_u64 v[164:165], s[12:13], 0, v[164:165]
	v_lshl_add_u64 v[164:165], v[164:165], 0, v[160:161]
	global_store_dwordx4 v[164:165], v[148:151], off offset:2048
	v_or_b32_e32 v172, 16, v162
	v_ashrrev_i32_e32 v173, 31, v172
	v_mul_f32_e32 v148, 0xbfb8aa3b, v104
	v_mul_f32_e32 v149, 0xbfb8aa3b, v105
	v_exp_f32_e32 v148, v148
	v_exp_f32_e32 v149, v149
	v_mul_f32_e32 v150, 0xbfb8aa3b, v106
	v_mul_f32_e32 v151, 0xbfb8aa3b, v107
	v_exp_f32_e32 v150, v150
	v_exp_f32_e32 v151, v151
	v_add_f32_e32 v148, 1.0, v148
	v_add_f32_e32 v149, 1.0, v149
	v_rcp_f32_e32 v148, v148
	v_rcp_f32_e32 v149, v149
	v_add_f32_e32 v150, 1.0, v150
	v_add_f32_e32 v151, 1.0, v151
	v_rcp_f32_e32 v150, v150
	v_rcp_f32_e32 v151, v151
	v_pk_mul_f32 v[164:165], v[104:105], v[148:149]
	v_mul_f32_e32 v148, 0xbfb8aa3b, v96
	v_mul_f32_e32 v149, 0xbfb8aa3b, v97
	v_exp_f32_e32 v148, v148
	v_exp_f32_e32 v149, v149
	v_pk_mul_f32 v[166:167], v[106:107], v[150:151]
	v_mul_f32_e32 v150, 0xbfb8aa3b, v98
	v_mul_f32_e32 v151, 0xbfb8aa3b, v99
	v_exp_f32_e32 v150, v150
	v_exp_f32_e32 v151, v151
	v_add_f32_e32 v148, 1.0, v148
	v_add_f32_e32 v149, 1.0, v149
	v_rcp_f32_e32 v148, v148
	v_rcp_f32_e32 v149, v149
	v_add_f32_e32 v150, 1.0, v150
	v_add_f32_e32 v151, 1.0, v151
	v_rcp_f32_e32 v150, v150
	v_rcp_f32_e32 v151, v151
	v_pk_mul_f32 v[168:169], v[96:97], v[148:149]
	v_lshlrev_b64 v[148:149], 11, v[172:173]
	v_lshl_add_u64 v[148:149], s[50:51], 0, v[148:149]
	v_lshl_add_u64 v[148:149], v[148:149], 0, v[160:161]
	v_pk_mul_f32 v[170:171], v[98:99], v[150:151]
	s_waitcnt vmcnt(5)
	v_mov_b32_e32 v148, v192
	v_mov_b32_e32 v149, v193
	v_mov_b32_e32 v150, v194
	v_mov_b32_e32 v151, v195
	v_add_u32_e32 v255, 0x50000, v187
	global_load_dwordx4 v[192:195], v255, s[50:51]
	v_mov_b32_e32 v174, v211
	v_mov_b32_e32 v175, v211
	v_mov_b32_e32 v176, v211
	v_mov_b32_e32 v177, v211
	v_mov_b32_e32 v178, v211
	v_mov_b32_e32 v180, v211
	v_pk_mul_f32 v[166:167], v[110:111], v[166:167]
	v_pk_mul_f32 v[170:171], v[102:103], v[170:171]
	v_cndmask_b32_e64 v163, v148, v144, s[4:5]
	v_cndmask_b32_e64 v144, v144, v148, s[0:1]
	s_nop 0
	v_mov_b32_dpp v174, v163 row_ror:1 row_mask:0xf bank_mask:0xf
	v_mov_b32_e32 v163, v211
	s_nop 1
	v_mov_b32_dpp v163, v144 row_ror:2 row_mask:0xf bank_mask:0xf
	v_cndmask_b32_e64 v144, v149, v145, s[4:5]
	v_cndmask_b32_e64 v145, v145, v149, s[0:1]
	s_nop 0
	v_mov_b32_dpp v175, v144 row_ror:1 row_mask:0xf bank_mask:0xf
	v_mov_b32_dpp v176, v145 row_ror:2 row_mask:0xf bank_mask:0xf
	v_cndmask_b32_e64 v144, v150, v146, s[4:5]
	v_cndmask_b32_e64 v145, v146, v150, s[0:1]
	s_nop 0
	v_mov_b32_dpp v177, v144 row_ror:1 row_mask:0xf bank_mask:0xf
	v_mov_b32_dpp v178, v145 row_ror:2 row_mask:0xf bank_mask:0xf
	v_cndmask_b32_e64 v144, v151, v147, s[4:5]
	v_cndmask_b32_e64 v145, v147, v151, s[0:1]
	v_pk_mul_f32 v[146:147], v[100:101], v[168:169]
	v_mov_b32_dpp v179, v144 row_ror:1 row_mask:0xf bank_mask:0xf
	v_mov_b32_dpp v180, v145 row_ror:2 row_mask:0xf bank_mask:0xf
	v_lshlrev_b32_e32 v145, 16, v174
	v_lshlrev_b32_e32 v144, 16, v148
	v_lshlrev_b32_e32 v168, 16, v163
	v_pk_mul_f32 v[144:145], v[156:157], v[144:145]
	v_and_b32_e32 v163, 0xffff0000, v163
	v_fma_f32 v145, v136, v168, v145
	v_add_f32_e32 v168, v144, v145
	v_and_b32_e32 v145, 0xffff0000, v174
	v_and_b32_e32 v144, 0xffff0000, v148
	v_pk_mul_f32 v[144:145], v[140:141], v[144:145]
	v_lshlrev_b32_e32 v169, 16, v176
	v_fma_f32 v145, v137, v163, v145
	v_add_f32_e32 v163, v144, v145
	v_lshlrev_b32_e32 v145, 16, v175
	v_lshlrev_b32_e32 v144, 16, v149
	v_pk_mul_f32 v[144:145], v[152:153], v[144:145]
	v_and_b32_e32 v174, 0xffff0000, v176
	v_fma_f32 v145, v138, v169, v145
	v_add_f32_e32 v169, v144, v145
	v_and_b32_e32 v145, 0xffff0000, v175
	v_and_b32_e32 v144, 0xffff0000, v149
	v_pk_mul_f32 v[144:145], v[142:143], v[144:145]
	v_lshlrev_b32_e32 v175, 16, v178
	v_fma_f32 v145, v139, v174, v145
	v_add_f32_e32 v174, v144, v145
	v_lshlrev_b32_e32 v145, 16, v177
	v_lshlrev_b32_e32 v144, 16, v150
	v_pk_mul_f32 v[144:145], v[154:155], v[144:145]
	v_and_b32_e32 v176, 0xffff0000, v178
	v_fma_f32 v145, v112, v175, v145
	v_add_f32_e32 v175, v144, v145
	v_and_b32_e32 v145, 0xffff0000, v177
	v_and_b32_e32 v144, 0xffff0000, v150
	v_pk_mul_f32 v[144:145], v[116:117], v[144:145]
	v_lshlrev_b32_e32 v177, 16, v180
	v_fma_f32 v145, v113, v176, v145
	v_add_f32_e32 v176, v144, v145
	v_lshlrev_b32_e32 v145, 16, v179
	v_lshlrev_b32_e32 v144, 16, v151
	v_pk_mul_f32 v[144:145], v[158:159], v[144:145]
	v_and_b32_e32 v178, 0xffff0000, v180
	v_fma_f32 v145, v114, v177, v145
	v_add_f32_e32 v177, v144, v145
	v_and_b32_e32 v145, 0xffff0000, v179
	v_and_b32_e32 v144, 0xffff0000, v151
	v_pk_mul_f32 v[144:145], v[118:119], v[144:145]
	v_mul_f32_e32 v146, v146, v175
	v_fma_f32 v145, v115, v178, v145
	v_add_f32_e32 v178, v144, v145
	v_pk_mul_f32 v[144:145], v[108:109], v[164:165]
	v_lshlrev_b64 v[164:165], 12, v[172:173]
	v_mul_f32_e32 v144, v144, v168
	v_mul_f32_e32 v145, v145, v163
	v_cvt_pk_bf16_f32 v144, v144, v145
	v_mul_f32_e32 v145, v166, v169
	v_mul_f32_e32 v147, v147, v176
	v_lshl_add_u64 v[164:165], s[12:13], 0, v[164:165]
	v_mul_f32_e32 v163, v167, v174
	v_cvt_pk_bf16_f32 v145, v145, v163
	v_cvt_pk_bf16_f32 v146, v146, v147
	v_mul_f32_e32 v147, v170, v177
	v_lshl_add_u64 v[164:165], v[164:165], 0, v[160:161]
	v_mul_f32_e32 v163, v171, v178
	v_cvt_pk_bf16_f32 v147, v147, v163
	global_store_dwordx4 v[164:165], v[144:147], off offset:2048
	v_or_b32_e32 v172, 32, v162
	v_ashrrev_i32_e32 v173, 31, v172
	v_mul_f32_e32 v144, 0xbfb8aa3b, v88
	v_mul_f32_e32 v145, 0xbfb8aa3b, v89
	v_exp_f32_e32 v144, v144
	v_exp_f32_e32 v145, v145
	v_mul_f32_e32 v146, 0xbfb8aa3b, v90
	v_mul_f32_e32 v147, 0xbfb8aa3b, v91
	v_exp_f32_e32 v146, v146
	v_exp_f32_e32 v147, v147
	v_add_f32_e32 v144, 1.0, v144
	v_add_f32_e32 v145, 1.0, v145
	v_rcp_f32_e32 v144, v144
	v_rcp_f32_e32 v145, v145
	v_add_f32_e32 v146, 1.0, v146
	v_add_f32_e32 v147, 1.0, v147
	v_rcp_f32_e32 v146, v146
	v_rcp_f32_e32 v147, v147
	v_pk_mul_f32 v[164:165], v[88:89], v[144:145]
	v_mul_f32_e32 v144, 0xbfb8aa3b, v80
	v_mul_f32_e32 v145, 0xbfb8aa3b, v81
	v_exp_f32_e32 v144, v144
	v_exp_f32_e32 v145, v145
	v_pk_mul_f32 v[166:167], v[90:91], v[146:147]
	v_mul_f32_e32 v146, 0xbfb8aa3b, v82
	v_mul_f32_e32 v147, 0xbfb8aa3b, v83
	v_exp_f32_e32 v146, v146
	v_exp_f32_e32 v147, v147
	v_add_f32_e32 v144, 1.0, v144
	v_add_f32_e32 v145, 1.0, v145
	v_rcp_f32_e32 v144, v144
	v_rcp_f32_e32 v145, v145
	v_add_f32_e32 v146, 1.0, v146
	v_add_f32_e32 v147, 1.0, v147
	v_rcp_f32_e32 v146, v146
	v_rcp_f32_e32 v147, v147
	v_pk_mul_f32 v[168:169], v[80:81], v[144:145]
	v_lshlrev_b64 v[144:145], 11, v[172:173]
	v_lshl_add_u64 v[144:145], s[50:51], 0, v[144:145]
	v_lshl_add_u64 v[144:145], v[144:145], 0, v[160:161]
	v_pk_mul_f32 v[170:171], v[82:83], v[146:147]
	s_waitcnt vmcnt(6)
	v_mov_b32_e32 v144, v196
	v_mov_b32_e32 v145, v197
	v_mov_b32_e32 v146, v198
	v_mov_b32_e32 v147, v199
	v_add_u32_e32 v255, 0x58000, v187
	global_load_dwordx4 v[196:199], v255, s[50:51]
	v_mov_b32_e32 v174, v211
	v_mov_b32_e32 v175, v211
	v_mov_b32_e32 v176, v211
	v_mov_b32_e32 v177, v211
	v_mov_b32_e32 v178, v211
	v_mov_b32_e32 v179, v211
	v_mov_b32_e32 v180, v211
	v_pk_mul_f32 v[166:167], v[94:95], v[166:167]
	v_pk_mul_f32 v[170:171], v[86:87], v[170:171]
	v_cndmask_b32_e64 v163, v144, v148, s[4:5]
	v_cndmask_b32_e64 v148, v148, v144, s[0:1]
	s_nop 0
	v_mov_b32_dpp v174, v163 row_ror:1 row_mask:0xf bank_mask:0xf
	v_mov_b32_e32 v163, v211
	s_nop 1
	v_mov_b32_dpp v163, v148 row_ror:2 row_mask:0xf bank_mask:0xf
	v_cndmask_b32_e64 v148, v145, v149, s[4:5]
	v_cndmask_b32_e64 v149, v149, v145, s[0:1]
	s_nop 0
	v_mov_b32_dpp v175, v148 row_ror:1 row_mask:0xf bank_mask:0xf
	v_mov_b32_dpp v176, v149 row_ror:2 row_mask:0xf bank_mask:0xf
	v_cndmask_b32_e64 v148, v146, v150, s[4:5]
	v_cndmask_b32_e64 v149, v150, v146, s[0:1]
	s_nop 0
	v_mov_b32_dpp v177, v148 row_ror:1 row_mask:0xf bank_mask:0xf
	v_mov_b32_dpp v178, v149 row_ror:2 row_mask:0xf bank_mask:0xf
	v_cndmask_b32_e64 v148, v147, v151, s[4:5]
	v_cndmask_b32_e64 v149, v151, v147, s[0:1]
	v_pk_mul_f32 v[150:151], v[84:85], v[168:169]
	v_mov_b32_dpp v179, v148 row_ror:1 row_mask:0xf bank_mask:0xf
	v_mov_b32_dpp v180, v149 row_ror:2 row_mask:0xf bank_mask:0xf
	v_lshlrev_b32_e32 v149, 16, v174
	v_lshlrev_b32_e32 v148, 16, v144
	v_lshlrev_b32_e32 v168, 16, v163
	v_pk_mul_f32 v[148:149], v[156:157], v[148:149]
	v_and_b32_e32 v163, 0xffff0000, v163
	v_fma_f32 v149, v136, v168, v149
	v_add_f32_e32 v168, v148, v149
	v_and_b32_e32 v149, 0xffff0000, v174
	v_and_b32_e32 v148, 0xffff0000, v144
	v_pk_mul_f32 v[148:149], v[140:141], v[148:149]
	v_lshlrev_b32_e32 v169, 16, v176
	v_fma_f32 v149, v137, v163, v149
	v_add_f32_e32 v163, v148, v149
	v_lshlrev_b32_e32 v149, 16, v175
	v_lshlrev_b32_e32 v148, 16, v145
	v_pk_mul_f32 v[148:149], v[152:153], v[148:149]
	v_and_b32_e32 v174, 0xffff0000, v176
	v_fma_f32 v149, v138, v169, v149
	v_add_f32_e32 v169, v148, v149
	v_and_b32_e32 v149, 0xffff0000, v175
	v_and_b32_e32 v148, 0xffff0000, v145
	v_pk_mul_f32 v[148:149], v[142:143], v[148:149]
	v_lshlrev_b32_e32 v175, 16, v178
	v_fma_f32 v149, v139, v174, v149
	v_add_f32_e32 v174, v148, v149
	v_lshlrev_b32_e32 v149, 16, v177
	v_lshlrev_b32_e32 v148, 16, v146
	v_pk_mul_f32 v[148:149], v[154:155], v[148:149]
	v_and_b32_e32 v176, 0xffff0000, v178
	v_fma_f32 v149, v112, v175, v149
	v_add_f32_e32 v175, v148, v149
	v_and_b32_e32 v149, 0xffff0000, v177
	v_and_b32_e32 v148, 0xffff0000, v146
	v_pk_mul_f32 v[148:149], v[116:117], v[148:149]
	v_lshlrev_b32_e32 v177, 16, v180
	v_fma_f32 v149, v113, v176, v149
	v_add_f32_e32 v176, v148, v149
	v_lshlrev_b32_e32 v149, 16, v179
	v_lshlrev_b32_e32 v148, 16, v147
	v_pk_mul_f32 v[148:149], v[158:159], v[148:149]
	v_and_b32_e32 v178, 0xffff0000, v180
	v_fma_f32 v149, v114, v177, v149
	v_add_f32_e32 v177, v148, v149
	v_and_b32_e32 v149, 0xffff0000, v179
	v_and_b32_e32 v148, 0xffff0000, v147
	v_pk_mul_f32 v[148:149], v[118:119], v[148:149]
	v_mul_f32_e32 v150, v150, v175
	v_fma_f32 v149, v115, v178, v149
	v_add_f32_e32 v178, v148, v149
	v_pk_mul_f32 v[148:149], v[92:93], v[164:165]
	v_mul_f32_e32 v151, v151, v176
	v_mul_f32_e32 v148, v148, v168
	v_mul_f32_e32 v149, v149, v163
	v_or_b32_e32 v168, 48, v162
	v_cvt_pk_bf16_f32 v148, v148, v149
	v_mul_f32_e32 v149, v166, v169
	v_mul_f32_e32 v163, v167, v174
	v_lshlrev_b64 v[164:165], 12, v[172:173]
	v_ashrrev_i32_e32 v169, 31, v168
	v_cvt_pk_bf16_f32 v149, v149, v163
	v_cvt_pk_bf16_f32 v150, v150, v151
	v_mul_f32_e32 v151, v170, v177
	v_mul_f32_e32 v163, v171, v178
	v_lshl_add_u64 v[164:165], s[12:13], 0, v[164:165]
	v_lshlrev_b64 v[170:171], 11, v[168:169]
	v_lshl_add_u64 v[164:165], v[164:165], 0, v[160:161]
	v_lshl_add_u64 v[170:171], s[50:51], 0, v[170:171]
	v_cvt_pk_bf16_f32 v151, v151, v163
	global_store_dwordx4 v[164:165], v[148:151], off offset:2048
	v_lshl_add_u64 v[170:171], v[170:171], 0, v[160:161]
	s_waitcnt vmcnt(7)
	v_mov_b32_e32 v176, v228
	v_mov_b32_e32 v177, v229
	v_mov_b32_e32 v178, v230
	v_mov_b32_e32 v179, v231
	v_mul_f32_e32 v148, 0xbfb8aa3b, v72
	v_mul_f32_e32 v149, 0xbfb8aa3b, v73
	v_exp_f32_e32 v148, v148
	v_exp_f32_e32 v149, v149
	v_mul_f32_e32 v150, 0xbfb8aa3b, v74
	v_mul_f32_e32 v151, 0xbfb8aa3b, v75
	v_add_f32_e32 v148, 1.0, v148
	v_add_f32_e32 v149, 1.0, v149
	v_rcp_f32_e32 v148, v148
	v_rcp_f32_e32 v149, v149
	v_exp_f32_e32 v150, v150
	v_exp_f32_e32 v151, v151
	v_mov_b32_e32 v170, v211
	v_pk_mul_f32 v[164:165], v[72:73], v[148:149]
	v_mul_f32_e32 v148, 0xbfb8aa3b, v64
	v_mul_f32_e32 v149, 0xbfb8aa3b, v65
	v_exp_f32_e32 v148, v148
	v_exp_f32_e32 v149, v149
	v_add_f32_e32 v150, 1.0, v150
	v_add_f32_e32 v151, 1.0, v151
	v_add_f32_e32 v148, 1.0, v148
	v_add_f32_e32 v149, 1.0, v149
	v_rcp_f32_e32 v148, v148
	v_rcp_f32_e32 v149, v149
	v_rcp_f32_e32 v150, v150
	v_rcp_f32_e32 v151, v151
	v_mov_b32_e32 v172, v211
	v_mov_b32_e32 v173, v211
	v_mov_b32_e32 v174, v211
	v_mov_b32_e32 v175, v211
	v_pk_mul_f32 v[148:149], v[64:65], v[148:149]
	v_pk_mul_f32 v[166:167], v[74:75], v[150:151]
	v_mul_f32_e32 v150, 0xbfb8aa3b, v66
	v_mul_f32_e32 v151, 0xbfb8aa3b, v67
	v_pk_mul_f32 v[182:183], v[68:69], v[148:149]
	v_exp_f32_e32 v150, v150
	v_exp_f32_e32 v151, v151
	v_pk_mul_f32 v[164:165], v[76:77], v[164:165]
	v_pk_mul_f32 v[166:167], v[78:79], v[166:167]
	v_add_f32_e32 v150, 1.0, v150
	v_add_f32_e32 v151, 1.0, v151
	v_rcp_f32_e32 v150, v150
	v_rcp_f32_e32 v151, v151
	v_cndmask_b32_e64 v163, v176, v144, s[4:5]
	v_cndmask_b32_e64 v144, v144, v176, s[0:1]
	s_nop 0
	v_mov_b32_dpp v170, v163 row_ror:1 row_mask:0xf bank_mask:0xf
	v_mov_b32_e32 v163, v211
	v_and_b32_e32 v171, 0xffff0000, v170
	v_pk_mul_f32 v[150:151], v[66:67], v[150:151]
	v_mov_b32_dpp v163, v144 row_ror:2 row_mask:0xf bank_mask:0xf
	v_cndmask_b32_e64 v144, v177, v145, s[4:5]
	v_cndmask_b32_e64 v145, v145, v177, s[0:1]
	v_lshlrev_b32_e32 v148, 16, v163
	v_mov_b32_dpp v172, v144 row_ror:1 row_mask:0xf bank_mask:0xf
	v_mov_b32_dpp v173, v145 row_ror:2 row_mask:0xf bank_mask:0xf
	v_cndmask_b32_e64 v144, v178, v146, s[4:5]
	v_cndmask_b32_e64 v145, v146, v178, s[0:1]
	v_pk_mul_f32 v[180:181], v[70:71], v[150:151]
	v_mov_b32_dpp v174, v144 row_ror:1 row_mask:0xf bank_mask:0xf
	v_mov_b32_dpp v175, v145 row_ror:2 row_mask:0xf bank_mask:0xf
	v_cndmask_b32_e64 v144, v179, v147, s[4:5]
	v_cndmask_b32_e64 v145, v147, v179, s[0:1]
	s_nop 0
	v_mov_b32_dpp v184, v144 row_ror:1 row_mask:0xf bank_mask:0xf
	v_mov_b32_dpp v185, v145 row_ror:2 row_mask:0xf bank_mask:0xf
	v_lshlrev_b32_e32 v145, 16, v170
	v_lshlrev_b32_e32 v144, 16, v176
	v_pk_mul_f32 v[146:147], v[156:157], v[144:145]
	v_and_b32_e32 v170, 0xffff0000, v176
	v_fma_f32 v145, v136, v148, v147
	v_add_f32_e32 v186, v146, v145
	v_and_b32_e32 v145, 0xffff0000, v163
	v_pk_mul_f32 v[146:147], v[140:141], v[170:171]
	s_nop 0
	v_fma_f32 v145, v137, v145, v147
	v_add_f32_e32 v163, v146, v145
	v_lshlrev_b32_e32 v147, 16, v172
	v_lshlrev_b32_e32 v146, 16, v177
	v_lshlrev_b32_e32 v145, 16, v173
	v_pk_mul_f32 v[148:149], v[152:153], v[146:147]
	v_mul_f32_e32 v163, v165, v163
	v_fma_f32 v145, v138, v145, v149
	v_add_f32_e32 v147, v148, v145
	v_and_b32_e32 v145, 0xffff0000, v173
	v_and_b32_e32 v173, 0xffff0000, v172
	v_and_b32_e32 v172, 0xffff0000, v177
	v_pk_mul_f32 v[148:149], v[142:143], v[172:173]
	v_mul_f32_e32 v147, v166, v147
	v_fma_f32 v145, v139, v145, v149
	v_add_f32_e32 v171, v148, v145
	v_lshlrev_b32_e32 v149, 16, v174
	v_lshlrev_b32_e32 v148, 16, v178
	v_lshlrev_b32_e32 v145, 16, v175
	v_pk_mul_f32 v[150:151], v[154:155], v[148:149]
	s_nop 0
	v_fma_f32 v145, v112, v145, v151
	v_add_f32_e32 v149, v150, v145
	v_and_b32_e32 v145, 0xffff0000, v175
	v_and_b32_e32 v175, 0xffff0000, v174
	v_and_b32_e32 v174, 0xffff0000, v178
	v_pk_mul_f32 v[150:151], v[116:117], v[174:175]
	s_nop 0
	v_fma_f32 v145, v113, v145, v151
	v_add_f32_e32 v173, v150, v145
	v_lshlrev_b32_e32 v151, 16, v184
	v_lshlrev_b32_e32 v150, 16, v179
	v_lshlrev_b32_e32 v145, 16, v185
	v_pk_mul_f32 v[176:177], v[158:159], v[150:151]
	s_nop 0
	v_fma_f32 v145, v114, v145, v177
	v_add_f32_e32 v151, v176, v145
	v_and_b32_e32 v177, 0xffff0000, v184
	v_and_b32_e32 v176, 0xffff0000, v179
	v_and_b32_e32 v145, 0xffff0000, v185
	v_pk_mul_f32 v[178:179], v[118:119], v[176:177]
	s_nop 0
	v_fma_f32 v145, v115, v145, v179
	v_add_f32_e32 v175, v178, v145
	v_bitop3_b32 v145, v162, s16, 48 bitop3:0xc8
	v_mul_f32_e32 v162, v164, v186
	v_cvt_pk_bf16_f32 v162, v162, v163
	v_mul_f32_e32 v163, v167, v171
	v_lshlrev_b64 v[166:167], 12, v[168:169]
	v_lshl_add_u64 v[166:167], s[12:13], 0, v[166:167]
	s_movk_i32 s16, 0x7fd
	v_cvt_pk_bf16_f32 v163, v147, v163
	v_mul_f32_e32 v147, v182, v149
	v_mul_f32_e32 v149, v183, v173
	v_lshl_add_u64 v[166:167], v[166:167], 0, v[160:161]
	v_cmp_lt_u32_e32 vcc, s16, v145
	v_cvt_pk_bf16_f32 v164, v147, v149
	v_mul_f32_e32 v147, v180, v151
	v_mul_f32_e32 v149, v181, v175
	v_cvt_pk_bf16_f32 v165, v147, v149
	global_store_dwordx4 v[166:167], v[162:165], off offset:2048
	s_and_saveexec_b64 s[40:41], vcc
	s_cbranch_execz .LBB0_316
	v_lshrrev_b32_e32 v147, 21, v169
	v_add_u32_e32 v147, v168, v147
	v_ashrrev_i32_e32 v162, 11, v147
	v_ashrrev_i32_e32 v163, 31, v162
	v_add_u32_e32 v164, 0xfffff802, v145
	v_mov_b32_e32 v165, v211
	v_lshlrev_b64 v[162:163], 13, v[162:163]
	v_lshl_add_u64 v[162:163], s[18:19], 0, v[162:163]
	v_lshlrev_b64 v[164:165], 12, v[164:165]
	v_lshl_add_u64 v[162:163], v[162:163], 0, v[164:165]
	v_lshl_add_u64 v[162:163], v[210:211], 2, v[162:163]
	v_mov_b32_e32 v145, v170
	v_mov_b32_e32 v147, v172
	v_mov_b32_e32 v149, v174
	v_mov_b32_e32 v151, v176
	global_store_dwordx4 v[162:163], v[144:147], off
	global_store_dwordx4 v[162:163], v[148:151], off offset:16
.LBB0_316:
	s_or_b64 exec, exec, s[40:41]
	s_addk_i32 s11, 0x80
	s_and_b32 s16, s11, 0x7c0
	s_cmp_lg_u32 s16, 0
	s_cselect_b64 s[16:17], -1, 0
	s_and_b64 s[16:17], s[8:9], s[16:17]
	v_mov_b32_e32 v148, 0
	v_mov_b32_e32 v149, 0
	v_mov_b32_e32 v150, 0
	v_mov_b32_e32 v151, 0
	v_mov_b32_e32 v148, v250
	v_mov_b32_e32 v149, v251
	v_mov_b32_e32 v150, v252
	v_mov_b32_e32 v151, v253
	v_mul_f32_e32 v144, 0xbfb8aa3b, v56
	v_mul_f32_e32 v145, 0xbfb8aa3b, v57
	v_exp_f32_e32 v144, v144
	v_exp_f32_e32 v145, v145
	v_mul_f32_e32 v146, 0xbfb8aa3b, v58
	v_mul_f32_e32 v147, 0xbfb8aa3b, v59
	v_exp_f32_e32 v146, v146
	v_exp_f32_e32 v147, v147
	v_add_f32_e32 v144, 1.0, v144
	v_add_f32_e32 v145, 1.0, v145
	v_rcp_f32_e32 v144, v144
	v_rcp_f32_e32 v145, v145
	v_add_f32_e32 v146, 1.0, v146
	v_add_f32_e32 v147, 1.0, v147
	v_rcp_f32_e32 v146, v146
	v_rcp_f32_e32 v147, v147
	v_pk_mul_f32 v[164:165], v[56:57], v[144:145]
	v_mul_f32_e32 v144, 0xbfb8aa3b, v48
	v_mul_f32_e32 v145, 0xbfb8aa3b, v49
	v_exp_f32_e32 v144, v144
	v_exp_f32_e32 v145, v145
	v_pk_mul_f32 v[166:167], v[58:59], v[146:147]
	v_mul_f32_e32 v146, 0xbfb8aa3b, v50
	v_mul_f32_e32 v147, 0xbfb8aa3b, v51
	v_exp_f32_e32 v146, v146
	v_exp_f32_e32 v147, v147
	v_add_f32_e32 v144, 1.0, v144
	v_add_f32_e32 v145, 1.0, v145
	v_rcp_f32_e32 v144, v144
	v_rcp_f32_e32 v145, v145
	v_or_b32_e32 v162, s11, v233
	v_add_f32_e32 v146, 1.0, v146
	v_add_f32_e32 v147, 1.0, v147
	v_rcp_f32_e32 v146, v146
	v_rcp_f32_e32 v147, v147
	v_ashrrev_i32_e32 v163, 31, v162
	v_pk_mul_f32 v[168:169], v[48:49], v[144:145]
	v_lshlrev_b64 v[144:145], 11, v[162:163]
	v_lshl_add_u64 v[144:145], s[50:51], 0, v[144:145]
	v_lshl_add_u64 v[144:145], v[144:145], 0, v[160:161]
	v_pk_mul_f32 v[170:171], v[50:51], v[146:147]
	s_waitcnt vmcnt(7)
	v_mov_b32_e32 v144, v246
	v_mov_b32_e32 v145, v247
	v_mov_b32_e32 v146, v248
	v_mov_b32_e32 v147, v249
	v_mov_b32_e32 v173, v211
	v_mov_b32_e32 v174, v211
	v_mov_b32_e32 v175, v211
	v_mov_b32_e32 v176, v211
	v_mov_b32_e32 v177, v211
	v_mov_b32_e32 v178, v211
	v_mov_b32_e32 v179, v211
	v_pk_mul_f32 v[166:167], v[62:63], v[166:167]
	v_pk_mul_f32 v[170:171], v[54:55], v[170:171]
	v_mov_b32_e32 v180, v211
	s_movk_i32 s8, 0x7ff
	v_cndmask_b32_e64 v172, v144, v148, s[4:5]
	v_cndmask_b32_e64 v148, v148, v144, s[0:1]
	s_nop 0
	v_mov_b32_dpp v173, v172 row_ror:1 row_mask:0xf bank_mask:0xf
	v_mov_b32_e32 v172, v211
	s_nop 1
	v_mov_b32_dpp v172, v148 row_ror:2 row_mask:0xf bank_mask:0xf
	v_cndmask_b32_e64 v148, v145, v149, s[4:5]
	v_cndmask_b32_e64 v149, v149, v145, s[0:1]
	s_nop 0
	v_mov_b32_dpp v174, v148 row_ror:1 row_mask:0xf bank_mask:0xf
	v_mov_b32_dpp v175, v149 row_ror:2 row_mask:0xf bank_mask:0xf
	v_cndmask_b32_e64 v148, v146, v150, s[4:5]
	v_cndmask_b32_e64 v149, v150, v146, s[0:1]
	s_nop 0
	v_mov_b32_dpp v176, v148 row_ror:1 row_mask:0xf bank_mask:0xf
	v_mov_b32_dpp v177, v149 row_ror:2 row_mask:0xf bank_mask:0xf
	v_cndmask_b32_e64 v148, v147, v151, s[4:5]
	v_cndmask_b32_e64 v149, v151, v147, s[0:1]
	v_pk_mul_f32 v[150:151], v[52:53], v[168:169]
	v_mov_b32_dpp v178, v148 row_ror:1 row_mask:0xf bank_mask:0xf
	v_mov_b32_dpp v179, v149 row_ror:2 row_mask:0xf bank_mask:0xf
	v_lshlrev_b32_e32 v148, 16, v144
	v_lshlrev_b32_e32 v149, 16, v173
	v_lshlrev_b32_e32 v168, 16, v172
	v_pk_mul_f32 v[148:149], v[156:157], v[148:149]
	v_and_b32_e32 v169, 0xffff0000, v172
	v_fma_f32 v149, v136, v168, v149
	v_add_f32_e32 v168, v148, v149
	v_and_b32_e32 v149, 0xffff0000, v173
	v_and_b32_e32 v148, 0xffff0000, v144
	v_pk_mul_f32 v[148:149], v[140:141], v[148:149]
	v_lshlrev_b32_e32 v172, 16, v175
	v_fma_f32 v149, v137, v169, v149
	v_add_f32_e32 v169, v148, v149
	v_lshlrev_b32_e32 v148, 16, v145
	v_lshlrev_b32_e32 v149, 16, v174
	v_pk_mul_f32 v[148:149], v[152:153], v[148:149]
	v_and_b32_e32 v173, 0xffff0000, v175
	v_fma_f32 v149, v138, v172, v149
	v_add_f32_e32 v172, v148, v149
	v_and_b32_e32 v149, 0xffff0000, v174
	v_and_b32_e32 v148, 0xffff0000, v145
	v_pk_mul_f32 v[148:149], v[142:143], v[148:149]
	v_lshlrev_b32_e32 v174, 16, v177
	v_fma_f32 v149, v139, v173, v149
	v_add_f32_e32 v173, v148, v149
	v_lshlrev_b32_e32 v148, 16, v146
	v_lshlrev_b32_e32 v149, 16, v176
	v_pk_mul_f32 v[148:149], v[154:155], v[148:149]
	v_and_b32_e32 v175, 0xffff0000, v177
	v_fma_f32 v149, v112, v174, v149
	v_add_f32_e32 v174, v148, v149
	v_and_b32_e32 v149, 0xffff0000, v176
	v_and_b32_e32 v148, 0xffff0000, v146
	v_pk_mul_f32 v[148:149], v[116:117], v[148:149]
	v_lshlrev_b32_e32 v176, 16, v179
	v_fma_f32 v149, v113, v175, v149
	v_add_f32_e32 v175, v148, v149
	v_lshlrev_b32_e32 v148, 16, v147
	v_lshlrev_b32_e32 v149, 16, v178
	v_pk_mul_f32 v[148:149], v[158:159], v[148:149]
	v_and_b32_e32 v177, 0xffff0000, v179
	v_fma_f32 v149, v114, v176, v149
	v_add_f32_e32 v176, v148, v149
	v_and_b32_e32 v149, 0xffff0000, v178
	v_and_b32_e32 v148, 0xffff0000, v147
	v_pk_mul_f32 v[148:149], v[118:119], v[148:149]
	v_mul_f32_e32 v150, v150, v174
	v_fma_f32 v149, v115, v177, v149
	v_add_f32_e32 v177, v148, v149
	v_pk_mul_f32 v[148:149], v[60:61], v[164:165]
	v_mul_f32_e32 v164, v167, v173
	v_mul_f32_e32 v148, v148, v168
	v_mul_f32_e32 v149, v149, v169
	v_cvt_pk_bf16_f32 v148, v148, v149
	v_mul_f32_e32 v149, v166, v172
	v_mul_f32_e32 v151, v151, v175
	v_cvt_pk_bf16_f32 v149, v149, v164
	v_cvt_pk_bf16_f32 v150, v150, v151
	v_mul_f32_e32 v151, v170, v176
	v_mul_f32_e32 v164, v171, v177
	v_cvt_pk_bf16_f32 v151, v151, v164
	v_lshlrev_b64 v[164:165], 12, v[162:163]
	v_lshl_add_u64 v[164:165], s[12:13], 0, v[164:165]
	v_lshl_add_u64 v[164:165], v[164:165], 0, v[160:161]
	global_store_dwordx4 v[164:165], v[148:151], off offset:2048
	v_or_b32_e32 v172, 16, v162
	v_ashrrev_i32_e32 v173, 31, v172
	v_mul_f32_e32 v148, 0xbfb8aa3b, v40
	v_mul_f32_e32 v149, 0xbfb8aa3b, v41
	v_exp_f32_e32 v148, v148
	v_exp_f32_e32 v149, v149
	v_mul_f32_e32 v150, 0xbfb8aa3b, v42
	v_mul_f32_e32 v151, 0xbfb8aa3b, v43
	v_exp_f32_e32 v150, v150
	v_exp_f32_e32 v151, v151
	v_add_f32_e32 v148, 1.0, v148
	v_add_f32_e32 v149, 1.0, v149
	v_rcp_f32_e32 v148, v148
	v_rcp_f32_e32 v149, v149
	v_add_f32_e32 v150, 1.0, v150
	v_add_f32_e32 v151, 1.0, v151
	v_rcp_f32_e32 v150, v150
	v_rcp_f32_e32 v151, v151
	v_pk_mul_f32 v[164:165], v[40:41], v[148:149]
	v_mul_f32_e32 v148, 0xbfb8aa3b, v32
	v_mul_f32_e32 v149, 0xbfb8aa3b, v33
	v_exp_f32_e32 v148, v148
	v_exp_f32_e32 v149, v149
	v_pk_mul_f32 v[166:167], v[42:43], v[150:151]
	v_mul_f32_e32 v150, 0xbfb8aa3b, v34
	v_mul_f32_e32 v151, 0xbfb8aa3b, v35
	v_exp_f32_e32 v150, v150
	v_exp_f32_e32 v151, v151
	v_add_f32_e32 v148, 1.0, v148
	v_add_f32_e32 v149, 1.0, v149
	v_rcp_f32_e32 v148, v148
	v_rcp_f32_e32 v149, v149
	v_add_f32_e32 v150, 1.0, v150
	v_add_f32_e32 v151, 1.0, v151
	v_rcp_f32_e32 v150, v150
	v_rcp_f32_e32 v151, v151
	v_pk_mul_f32 v[168:169], v[32:33], v[148:149]
	v_lshlrev_b64 v[148:149], 11, v[172:173]
	v_lshl_add_u64 v[148:149], s[50:51], 0, v[148:149]
	v_lshl_add_u64 v[148:149], v[148:149], 0, v[160:161]
	v_pk_mul_f32 v[170:171], v[34:35], v[150:151]
	s_waitcnt vmcnt(7)
	v_mov_b32_e32 v148, v188
	v_mov_b32_e32 v149, v189
	v_mov_b32_e32 v150, v190
	v_mov_b32_e32 v151, v191
	v_mov_b32_e32 v174, v211
	v_mov_b32_e32 v175, v211
	v_mov_b32_e32 v176, v211
	v_mov_b32_e32 v177, v211
	v_mov_b32_e32 v178, v211
	v_mov_b32_e32 v179, v211
	v_pk_mul_f32 v[166:167], v[46:47], v[166:167]
	v_pk_mul_f32 v[170:171], v[38:39], v[170:171]
	v_cndmask_b32_e64 v163, v148, v144, s[4:5]
	v_cndmask_b32_e64 v144, v144, v148, s[0:1]
	s_nop 0
	v_mov_b32_dpp v174, v163 row_ror:1 row_mask:0xf bank_mask:0xf
	v_mov_b32_e32 v163, v211
	s_nop 1
	v_mov_b32_dpp v163, v144 row_ror:2 row_mask:0xf bank_mask:0xf
	v_cndmask_b32_e64 v144, v149, v145, s[4:5]
	v_cndmask_b32_e64 v145, v145, v149, s[0:1]
	s_nop 0
	v_mov_b32_dpp v175, v144 row_ror:1 row_mask:0xf bank_mask:0xf
	v_mov_b32_dpp v176, v145 row_ror:2 row_mask:0xf bank_mask:0xf
	v_cndmask_b32_e64 v144, v150, v146, s[4:5]
	v_cndmask_b32_e64 v145, v146, v150, s[0:1]
	s_nop 0
	v_mov_b32_dpp v177, v144 row_ror:1 row_mask:0xf bank_mask:0xf
	v_mov_b32_dpp v178, v145 row_ror:2 row_mask:0xf bank_mask:0xf
	v_cndmask_b32_e64 v144, v151, v147, s[4:5]
	v_cndmask_b32_e64 v145, v147, v151, s[0:1]
	v_pk_mul_f32 v[146:147], v[36:37], v[168:169]
	v_mov_b32_dpp v179, v144 row_ror:1 row_mask:0xf bank_mask:0xf
	v_mov_b32_dpp v180, v145 row_ror:2 row_mask:0xf bank_mask:0xf
	v_lshlrev_b32_e32 v145, 16, v174
	v_lshlrev_b32_e32 v144, 16, v148
	v_lshlrev_b32_e32 v168, 16, v163
	v_pk_mul_f32 v[144:145], v[156:157], v[144:145]
	v_and_b32_e32 v163, 0xffff0000, v163
	v_fma_f32 v145, v136, v168, v145
	v_add_f32_e32 v168, v144, v145
	v_and_b32_e32 v145, 0xffff0000, v174
	v_and_b32_e32 v144, 0xffff0000, v148
	v_pk_mul_f32 v[144:145], v[140:141], v[144:145]
	v_lshlrev_b32_e32 v169, 16, v176
	v_fma_f32 v145, v137, v163, v145
	v_add_f32_e32 v163, v144, v145
	v_lshlrev_b32_e32 v145, 16, v175
	v_lshlrev_b32_e32 v144, 16, v149
	v_pk_mul_f32 v[144:145], v[152:153], v[144:145]
	v_and_b32_e32 v174, 0xffff0000, v176
	v_fma_f32 v145, v138, v169, v145
	v_add_f32_e32 v169, v144, v145
	v_and_b32_e32 v145, 0xffff0000, v175
	v_and_b32_e32 v144, 0xffff0000, v149
	v_pk_mul_f32 v[144:145], v[142:143], v[144:145]
	v_lshlrev_b32_e32 v175, 16, v178
	v_fma_f32 v145, v139, v174, v145
	v_add_f32_e32 v174, v144, v145
	v_lshlrev_b32_e32 v145, 16, v177
	v_lshlrev_b32_e32 v144, 16, v150
	v_pk_mul_f32 v[144:145], v[154:155], v[144:145]
	v_and_b32_e32 v176, 0xffff0000, v178
	v_fma_f32 v145, v112, v175, v145
	v_add_f32_e32 v175, v144, v145
	v_and_b32_e32 v145, 0xffff0000, v177
	v_and_b32_e32 v144, 0xffff0000, v150
	v_pk_mul_f32 v[144:145], v[116:117], v[144:145]
	v_lshlrev_b32_e32 v177, 16, v180
	v_fma_f32 v145, v113, v176, v145
	v_add_f32_e32 v176, v144, v145
	v_lshlrev_b32_e32 v145, 16, v179
	v_lshlrev_b32_e32 v144, 16, v151
	v_pk_mul_f32 v[144:145], v[158:159], v[144:145]
	v_and_b32_e32 v178, 0xffff0000, v180
	v_fma_f32 v145, v114, v177, v145
	v_add_f32_e32 v177, v144, v145
	v_and_b32_e32 v145, 0xffff0000, v179
	v_and_b32_e32 v144, 0xffff0000, v151
	v_pk_mul_f32 v[144:145], v[118:119], v[144:145]
	v_mul_f32_e32 v146, v146, v175
	v_fma_f32 v145, v115, v178, v145
	v_add_f32_e32 v178, v144, v145
	v_pk_mul_f32 v[144:145], v[44:45], v[164:165]
	v_lshlrev_b64 v[164:165], 12, v[172:173]
	v_mul_f32_e32 v144, v144, v168
	v_mul_f32_e32 v145, v145, v163
	v_cvt_pk_bf16_f32 v144, v144, v145
	v_mul_f32_e32 v145, v166, v169
	v_mul_f32_e32 v147, v147, v176
	v_lshl_add_u64 v[164:165], s[12:13], 0, v[164:165]
	v_mul_f32_e32 v163, v167, v174
	v_cvt_pk_bf16_f32 v145, v145, v163
	v_cvt_pk_bf16_f32 v146, v146, v147
	v_mul_f32_e32 v147, v170, v177
	v_lshl_add_u64 v[164:165], v[164:165], 0, v[160:161]
	v_mul_f32_e32 v163, v171, v178
	v_cvt_pk_bf16_f32 v147, v147, v163
	global_store_dwordx4 v[164:165], v[144:147], off offset:2048
	v_or_b32_e32 v172, 32, v162
	v_ashrrev_i32_e32 v173, 31, v172
	v_mul_f32_e32 v144, 0xbfb8aa3b, v24
	v_mul_f32_e32 v145, 0xbfb8aa3b, v25
	v_exp_f32_e32 v144, v144
	v_exp_f32_e32 v145, v145
	v_mul_f32_e32 v146, 0xbfb8aa3b, v26
	v_mul_f32_e32 v147, 0xbfb8aa3b, v27
	v_exp_f32_e32 v146, v146
	v_exp_f32_e32 v147, v147
	v_add_f32_e32 v144, 1.0, v144
	v_add_f32_e32 v145, 1.0, v145
	v_rcp_f32_e32 v144, v144
	v_rcp_f32_e32 v145, v145
	v_add_f32_e32 v146, 1.0, v146
	v_add_f32_e32 v147, 1.0, v147
	v_rcp_f32_e32 v146, v146
	v_rcp_f32_e32 v147, v147
	v_pk_mul_f32 v[164:165], v[24:25], v[144:145]
	v_mul_f32_e32 v144, 0xbfb8aa3b, v16
	v_mul_f32_e32 v145, 0xbfb8aa3b, v17
	v_exp_f32_e32 v144, v144
	v_exp_f32_e32 v145, v145
	v_pk_mul_f32 v[166:167], v[26:27], v[146:147]
	v_mul_f32_e32 v146, 0xbfb8aa3b, v18
	v_mul_f32_e32 v147, 0xbfb8aa3b, v19
	v_exp_f32_e32 v146, v146
	v_exp_f32_e32 v147, v147
	v_add_f32_e32 v144, 1.0, v144
	v_add_f32_e32 v145, 1.0, v145
	v_rcp_f32_e32 v144, v144
	v_rcp_f32_e32 v145, v145
	v_add_f32_e32 v146, 1.0, v146
	v_add_f32_e32 v147, 1.0, v147
	v_rcp_f32_e32 v146, v146
	v_rcp_f32_e32 v147, v147
	v_pk_mul_f32 v[168:169], v[16:17], v[144:145]
	v_lshlrev_b64 v[144:145], 11, v[172:173]
	v_lshl_add_u64 v[144:145], s[50:51], 0, v[144:145]
	v_lshl_add_u64 v[144:145], v[144:145], 0, v[160:161]
	v_pk_mul_f32 v[170:171], v[18:19], v[146:147]
	s_waitcnt vmcnt(6)
	v_mov_b32_e32 v144, v192
	v_mov_b32_e32 v145, v193
	v_mov_b32_e32 v146, v194
	v_mov_b32_e32 v147, v195
	v_mov_b32_e32 v174, v211
	v_mov_b32_e32 v175, v211
	v_mov_b32_e32 v176, v211
	v_mov_b32_e32 v177, v211
	v_mov_b32_e32 v178, v211
	v_mov_b32_e32 v179, v211
	v_mov_b32_e32 v180, v211
	v_pk_mul_f32 v[166:167], v[30:31], v[166:167]
	v_pk_mul_f32 v[170:171], v[22:23], v[170:171]
	v_cndmask_b32_e64 v163, v144, v148, s[4:5]
	v_cndmask_b32_e64 v148, v148, v144, s[0:1]
	s_nop 0
	v_mov_b32_dpp v174, v163 row_ror:1 row_mask:0xf bank_mask:0xf
	v_mov_b32_e32 v163, v211
	s_nop 1
	v_mov_b32_dpp v163, v148 row_ror:2 row_mask:0xf bank_mask:0xf
	v_cndmask_b32_e64 v148, v145, v149, s[4:5]
	v_cndmask_b32_e64 v149, v149, v145, s[0:1]
	s_nop 0
	v_mov_b32_dpp v175, v148 row_ror:1 row_mask:0xf bank_mask:0xf
	v_mov_b32_dpp v176, v149 row_ror:2 row_mask:0xf bank_mask:0xf
	v_cndmask_b32_e64 v148, v146, v150, s[4:5]
	v_cndmask_b32_e64 v149, v150, v146, s[0:1]
	s_nop 0
	v_mov_b32_dpp v177, v148 row_ror:1 row_mask:0xf bank_mask:0xf
	v_mov_b32_dpp v178, v149 row_ror:2 row_mask:0xf bank_mask:0xf
	v_cndmask_b32_e64 v148, v147, v151, s[4:5]
	v_cndmask_b32_e64 v149, v151, v147, s[0:1]
	v_pk_mul_f32 v[150:151], v[20:21], v[168:169]
	v_mov_b32_dpp v179, v148 row_ror:1 row_mask:0xf bank_mask:0xf
	v_mov_b32_dpp v180, v149 row_ror:2 row_mask:0xf bank_mask:0xf
	v_lshlrev_b32_e32 v149, 16, v174
	v_lshlrev_b32_e32 v148, 16, v144
	v_lshlrev_b32_e32 v168, 16, v163
	v_pk_mul_f32 v[148:149], v[156:157], v[148:149]
	v_and_b32_e32 v163, 0xffff0000, v163
	v_fma_f32 v149, v136, v168, v149
	v_add_f32_e32 v168, v148, v149
	v_and_b32_e32 v149, 0xffff0000, v174
	v_and_b32_e32 v148, 0xffff0000, v144
	v_pk_mul_f32 v[148:149], v[140:141], v[148:149]
	v_lshlrev_b32_e32 v169, 16, v176
	v_fma_f32 v149, v137, v163, v149
	v_add_f32_e32 v163, v148, v149
	v_lshlrev_b32_e32 v149, 16, v175
	v_lshlrev_b32_e32 v148, 16, v145
	v_pk_mul_f32 v[148:149], v[152:153], v[148:149]
	v_and_b32_e32 v174, 0xffff0000, v176
	v_fma_f32 v149, v138, v169, v149
	v_add_f32_e32 v169, v148, v149
	v_and_b32_e32 v149, 0xffff0000, v175
	v_and_b32_e32 v148, 0xffff0000, v145
	v_pk_mul_f32 v[148:149], v[142:143], v[148:149]
	v_lshlrev_b32_e32 v175, 16, v178
	v_fma_f32 v149, v139, v174, v149
	v_add_f32_e32 v174, v148, v149
	v_lshlrev_b32_e32 v149, 16, v177
	v_lshlrev_b32_e32 v148, 16, v146
	v_pk_mul_f32 v[148:149], v[154:155], v[148:149]
	v_and_b32_e32 v176, 0xffff0000, v178
	v_fma_f32 v149, v112, v175, v149
	v_add_f32_e32 v175, v148, v149
	v_and_b32_e32 v149, 0xffff0000, v177
	v_and_b32_e32 v148, 0xffff0000, v146
	v_pk_mul_f32 v[148:149], v[116:117], v[148:149]
	v_lshlrev_b32_e32 v177, 16, v180
	v_fma_f32 v149, v113, v176, v149
	v_add_f32_e32 v176, v148, v149
	v_lshlrev_b32_e32 v149, 16, v179
	v_lshlrev_b32_e32 v148, 16, v147
	v_pk_mul_f32 v[148:149], v[158:159], v[148:149]
	v_and_b32_e32 v178, 0xffff0000, v180
	v_fma_f32 v149, v114, v177, v149
	v_add_f32_e32 v177, v148, v149
	v_and_b32_e32 v149, 0xffff0000, v179
	v_and_b32_e32 v148, 0xffff0000, v147
	v_pk_mul_f32 v[148:149], v[118:119], v[148:149]
	v_mul_f32_e32 v150, v150, v175
	v_fma_f32 v149, v115, v178, v149
	v_add_f32_e32 v178, v148, v149
	v_pk_mul_f32 v[148:149], v[28:29], v[164:165]
	v_mul_f32_e32 v151, v151, v176
	v_mul_f32_e32 v148, v148, v168
	v_mul_f32_e32 v149, v149, v163
	v_or_b32_e32 v168, 48, v162
	v_cvt_pk_bf16_f32 v148, v148, v149
	v_mul_f32_e32 v149, v166, v169
	v_mul_f32_e32 v163, v167, v174
	v_lshlrev_b64 v[164:165], 12, v[172:173]
	v_ashrrev_i32_e32 v169, 31, v168
	v_cvt_pk_bf16_f32 v149, v149, v163
	v_cvt_pk_bf16_f32 v150, v150, v151
	v_mul_f32_e32 v151, v170, v177
	v_mul_f32_e32 v163, v171, v178
	v_lshl_add_u64 v[164:165], s[12:13], 0, v[164:165]
	v_lshlrev_b64 v[170:171], 11, v[168:169]
	v_lshl_add_u64 v[164:165], v[164:165], 0, v[160:161]
	v_lshl_add_u64 v[170:171], s[50:51], 0, v[170:171]
	v_cvt_pk_bf16_f32 v151, v151, v163
	global_store_dwordx4 v[164:165], v[148:151], off offset:2048
	v_lshl_add_u64 v[170:171], v[170:171], 0, v[160:161]
	s_waitcnt vmcnt(5)
	v_mov_b32_e32 v170, v196
	v_mov_b32_e32 v171, v197
	v_mov_b32_e32 v172, v198
	v_mov_b32_e32 v173, v199
	v_mul_f32_e32 v163, 0xbfb8aa3b, v0
	v_exp_f32_e32 v163, v163
	v_mov_b32_e32 v174, v211
	v_mov_b32_e32 v175, v211
	v_mov_b32_e32 v176, v211
	v_add_f32_e32 v163, 1.0, v163
	v_rcp_f32_e32 v164, v163
	v_mul_f32_e32 v163, 0xbfb8aa3b, v1
	v_exp_f32_e32 v163, v163
	v_mov_b32_e32 v177, v211
	v_mov_b32_e32 v178, v211
	v_mov_b32_e32 v179, v211
	v_add_f32_e32 v163, 1.0, v163
	v_rcp_f32_e32 v165, v163
	v_mul_f32_e32 v163, 0xbfb8aa3b, v2
	v_exp_f32_e32 v163, v163
	v_mov_b32_e32 v180, v211
	v_mul_f32_e32 v148, 0xbfb8aa3b, v8
	v_mul_f32_e32 v149, 0xbfb8aa3b, v9
	v_add_f32_e32 v163, 1.0, v163
	v_rcp_f32_e32 v166, v163
	v_mul_f32_e32 v163, 0xbfb8aa3b, v3
	v_exp_f32_e32 v163, v163
	v_exp_f32_e32 v148, v148
	v_exp_f32_e32 v149, v149
	v_mul_f32_e32 v150, 0xbfb8aa3b, v10
	v_add_f32_e32 v163, 1.0, v163
	v_rcp_f32_e32 v167, v163
	v_mul_f32_e32 v151, 0xbfb8aa3b, v11
	v_exp_f32_e32 v150, v150
	v_exp_f32_e32 v151, v151
	v_add_f32_e32 v148, 1.0, v148
	v_add_f32_e32 v149, 1.0, v149
	v_rcp_f32_e32 v148, v148
	v_rcp_f32_e32 v149, v149
	v_add_f32_e32 v150, 1.0, v150
	v_add_f32_e32 v151, 1.0, v151
	v_rcp_f32_e32 v150, v150
	v_rcp_f32_e32 v151, v151
	v_pk_mul_f32 v[148:149], v[8:9], v[148:149]
	v_pk_mul_f32 v[164:165], v[0:1], v[164:165]
	v_pk_mul_f32 v[166:167], v[2:3], v[166:167]
	v_pk_mul_f32 v[150:151], v[10:11], v[150:151]
	v_pk_mul_f32 v[164:165], v[4:5], v[164:165]
	v_pk_mul_f32 v[166:167], v[6:7], v[166:167]
	v_cndmask_b32_e64 v163, v170, v144, s[4:5]
	v_cndmask_b32_e64 v144, v144, v170, s[0:1]
	s_nop 0
	v_mov_b32_dpp v174, v163 row_ror:1 row_mask:0xf bank_mask:0xf
	v_mov_b32_e32 v163, v211
	s_nop 1
	v_mov_b32_dpp v163, v144 row_ror:2 row_mask:0xf bank_mask:0xf
	v_cndmask_b32_e64 v144, v171, v145, s[4:5]
	v_cndmask_b32_e64 v145, v145, v171, s[0:1]
	v_lshlrev_b32_e32 v181, 16, v163
	v_mov_b32_dpp v175, v144 row_ror:1 row_mask:0xf bank_mask:0xf
	v_mov_b32_dpp v176, v145 row_ror:2 row_mask:0xf bank_mask:0xf
	v_cndmask_b32_e64 v144, v172, v146, s[4:5]
	v_cndmask_b32_e64 v145, v146, v172, s[0:1]
	s_nop 0
	v_mov_b32_dpp v177, v144 row_ror:1 row_mask:0xf bank_mask:0xf
	v_mov_b32_dpp v178, v145 row_ror:2 row_mask:0xf bank_mask:0xf
	v_cndmask_b32_e64 v144, v173, v147, s[4:5]
	v_cndmask_b32_e64 v145, v147, v173, s[0:1]
	s_nop 0
	v_mov_b32_dpp v179, v144 row_ror:1 row_mask:0xf bank_mask:0xf
	v_mov_b32_dpp v180, v145 row_ror:2 row_mask:0xf bank_mask:0xf
	v_lshlrev_b32_e32 v145, 16, v174
	v_lshlrev_b32_e32 v144, 16, v170
	v_pk_mul_f32 v[146:147], v[156:157], v[144:145]
	v_and_b32_e32 v157, 0xffff0000, v174
	v_fma_f32 v136, v136, v181, v147
	v_and_b32_e32 v156, 0xffff0000, v170
	v_add_f32_e32 v145, v146, v136
	v_and_b32_e32 v136, 0xffff0000, v163
	v_pk_mul_f32 v[140:141], v[140:141], v[156:157]
	v_lshlrev_b32_e32 v147, 16, v175
	v_fma_f32 v136, v137, v136, v141
	v_lshlrev_b32_e32 v146, 16, v171
	v_add_f32_e32 v157, v140, v136
	v_lshlrev_b32_e32 v140, 16, v176
	v_pk_mul_f32 v[136:137], v[152:153], v[146:147]
	v_and_b32_e32 v141, 0xffff0000, v175
	v_fma_f32 v137, v138, v140, v137
	v_and_b32_e32 v140, 0xffff0000, v171
	v_add_f32_e32 v147, v136, v137
	v_and_b32_e32 v138, 0xffff0000, v176
	v_pk_mul_f32 v[136:137], v[142:143], v[140:141]
	v_lshlrev_b32_e32 v142, 16, v178
	v_fma_f32 v137, v139, v138, v137
	v_add_f32_e32 v141, v136, v137
	v_lshlrev_b32_e32 v137, 16, v177
	v_lshlrev_b32_e32 v136, 16, v172
	v_pk_mul_f32 v[138:139], v[154:155], v[136:137]
	v_and_b32_e32 v143, 0xffff0000, v177
	v_fma_f32 v112, v112, v142, v139
	v_and_b32_e32 v142, 0xffff0000, v172
	v_add_f32_e32 v137, v138, v112
	v_and_b32_e32 v112, 0xffff0000, v178
	v_pk_mul_f32 v[116:117], v[116:117], v[142:143]
	v_lshlrev_b32_e32 v139, 16, v179
	v_fma_f32 v112, v113, v112, v117
	v_lshlrev_b32_e32 v138, 16, v173
	v_add_f32_e32 v143, v116, v112
	v_lshlrev_b32_e32 v116, 16, v180
	v_pk_mul_f32 v[112:113], v[158:159], v[138:139]
	s_nop 0
	v_fma_f32 v113, v114, v116, v113
	v_add_f32_e32 v139, v112, v113
	v_and_b32_e32 v113, 0xffff0000, v179
	v_and_b32_e32 v112, 0xffff0000, v173
	v_and_b32_e32 v114, 0xffff0000, v180
	v_pk_mul_f32 v[116:117], v[118:119], v[112:113]
	s_nop 0
	v_fma_f32 v113, v115, v114, v117
	v_pk_mul_f32 v[114:115], v[12:13], v[148:149]
	v_add_f32_e32 v118, v116, v113
	v_pk_mul_f32 v[116:117], v[14:15], v[150:151]
	v_mul_f32_e32 v114, v114, v145
	v_mul_f32_e32 v115, v115, v157
	v_cvt_pk_bf16_f32 v114, v114, v115
	v_mul_f32_e32 v115, v116, v147
	v_mul_f32_e32 v116, v117, v141
	v_cvt_pk_bf16_f32 v115, v115, v116
	v_mul_f32_e32 v116, v164, v137
	v_mul_f32_e32 v117, v165, v143
	v_cvt_pk_bf16_f32 v116, v116, v117
	v_mul_f32_e32 v117, v166, v139
	v_mul_f32_e32 v118, v167, v118
	v_cvt_pk_bf16_f32 v117, v117, v118
	v_lshlrev_b64 v[118:119], 12, v[168:169]
	v_bitop3_b32 v113, v162, s8, 48 bitop3:0xc8
	v_lshl_add_u64 v[118:119], s[12:13], 0, v[118:119]
	s_movk_i32 s8, 0x7fd
	v_lshl_add_u64 v[118:119], v[118:119], 0, v[160:161]
	v_cmp_lt_u32_e32 vcc, s8, v113
	global_store_dwordx4 v[118:119], v[114:117], off offset:2048
	s_and_saveexec_b64 s[8:9], vcc
	s_cbranch_execz .LBB0_320
	v_lshrrev_b32_e32 v114, 21, v169
	v_add_u32_e32 v114, v168, v114
	v_ashrrev_i32_e32 v114, 11, v114
	v_ashrrev_i32_e32 v115, 31, v114
	v_add_u32_e32 v116, 0xfffff802, v113
	v_mov_b32_e32 v117, v211
	v_lshlrev_b64 v[114:115], 13, v[114:115]
	v_lshl_add_u64 v[114:115], s[18:19], 0, v[114:115]
	v_lshlrev_b64 v[116:117], 12, v[116:117]
	v_lshl_add_u64 v[114:115], v[114:115], 0, v[116:117]
	v_lshl_add_u64 v[114:115], v[210:211], 2, v[114:115]
	v_mov_b32_e32 v145, v156
	v_mov_b32_e32 v147, v140
	v_mov_b32_e32 v137, v142
	v_mov_b32_e32 v139, v112
	global_store_dwordx4 v[114:115], v[144:147], off
	global_store_dwordx4 v[114:115], v[136:139], off offset:16

.LBB0_502:
	s_lshl_b32 s0, s14, 8
	s_add_i32 s4, s0, s15
	s_lshl_b32 s1, s3, 5
	v_or_b32_e32 v130, s4, v233
	s_lshl_b32 s4, s51, 8
	s_or_b32 s1, s4, s1
	v_ashrrev_i32_e32 v131, 31, v130
	v_lshl_or_b32 v128, v144, 2, s1
	v_lshlrev_b64 v[132:133], 12, v[130:131]
	v_ashrrev_i32_e32 v129, 31, v128
	v_lshl_add_u64 v[134:135], s[44:45], 0, v[132:133]
	v_lshl_add_u64 v[142:143], v[128:129], 2, v[134:135]
	s_barrier
	v_lshl_add_u32 v198, v128, 2, v132
	global_load_dwordx4 v[182:185], v198, s[44:45] nt
	global_load_dwordx4 v[186:189], v198, s[44:45] offset:64 nt
	global_load_dwordx4 v[190:193], v198, s[44:45] offset:512 nt
	global_load_dwordx4 v[194:197], v198, s[44:45] offset:576 nt
	v_add_u32_e32 v199, 0x10000, v198
	global_load_dwordx4 v[202:205], v199, s[44:45] nt
	global_load_dwordx4 v[206:209], v199, s[44:45] offset:64 nt
	global_load_dwordx4 v[210:213], v199, s[44:45] offset:512 nt
	global_load_dwordx4 v[214:217], v199, s[44:45] offset:576 nt
	v_add_u32_e32 v199, 0x20000, v198
	global_load_dwordx4 v[234:237], v199, s[44:45] nt
	global_load_dwordx4 v[238:241], v199, s[44:45] offset:64 nt
	global_load_dwordx4 v[242:245], v199, s[44:45] offset:512 nt
	global_load_dwordx4 v[246:249], v199, s[44:45] offset:576 nt
	v_add_u32_e32 v199, 0x30000, v198
	global_load_dwordx4 v[218:221], v199, s[44:45] nt
	global_load_dwordx4 v[222:225], v199, s[44:45] offset:64 nt
	global_load_dwordx4 v[226:229], v199, s[44:45] offset:512 nt
	global_load_dwordx4 v[250:253], v199, s[44:45] offset:576 nt
	v_mbcnt_lo_u32_b32 v142, -1, 0
	v_mbcnt_hi_u32_b32 v142, -1, v142
	v_and_b32_e32 v145, 64, v142
	v_xor_b32_e32 v143, 16, v142
	v_add_u32_e32 v145, 64, v145
	v_cmp_lt_i32_e32 vcc, v143, v145
	v_xor_b32_e32 v154, 32, v142
	s_lshl_b32 s1, s15, 2
	v_cndmask_b32_e32 v143, v142, v143, vcc
	v_lshlrev_b32_e32 v171, 2, v143
	v_cmp_lt_i32_e32 vcc, v154, v145
	s_add_i32 s1, s1, 0
	s_lshl_b32 s3, s3, 10
	s_add_i32 s1, s1, s3
	v_lshl_add_u32 v173, v233, 2, s1
	s_waitcnt vmcnt(12)
	v_pk_add_f32 v[126:127], v[126:127], v[184:185]
	v_pk_add_f32 v[124:125], v[124:125], v[182:183]
	v_pk_add_f32 v[122:123], v[122:123], v[188:189]
	v_pk_add_f32 v[120:121], v[120:121], v[186:187]
	v_pk_add_f32 v[118:119], v[118:119], v[192:193]
	v_pk_add_f32 v[116:117], v[116:117], v[190:191]
	v_mul_f32_e32 v134, v125, v125
	v_mul_f32_e32 v135, v127, v127
	v_mul_f32_e32 v136, v121, v121
	v_mul_f32_e32 v137, v123, v123
	v_pk_add_f32 v[114:115], v[114:115], v[196:197]
	v_pk_add_f32 v[112:113], v[112:113], v[194:195]
	v_add_u32_e32 v199, 0x80000, v198
	global_load_dwordx4 v[182:185], v199, s[44:45] nt
	global_load_dwordx4 v[186:189], v199, s[44:45] offset:64 nt
	global_load_dwordx4 v[190:193], v199, s[44:45] offset:512 nt
	global_load_dwordx4 v[194:197], v199, s[44:45] offset:576 nt
	v_mul_f32_e32 v138, v117, v117
	v_mul_f32_e32 v139, v119, v119
	v_fmac_f32_e32 v134, v124, v124
	v_fmac_f32_e32 v135, v126, v126
	v_fmac_f32_e32 v136, v120, v120
	v_fmac_f32_e32 v137, v122, v122
	v_mul_f32_e32 v140, v113, v113
	v_mul_f32_e32 v141, v115, v115
	v_fmac_f32_e32 v138, v116, v116
	v_fmac_f32_e32 v139, v118, v118
	v_add_f32_e32 v134, v134, v135
	v_add_f32_e32 v135, v136, v137
	v_fmac_f32_e32 v140, v112, v112
	v_fmac_f32_e32 v141, v114, v114
	v_add_f32_e32 v136, v138, v139
	v_add_f32_e32 v134, v134, v135
	v_add_f32_e32 v137, v140, v141
	v_add_f32_e32 v134, v134, v136
	v_add_f32_e32 v134, v134, v137
	ds_bpermute_b32 v135, v171, v134
	v_cndmask_b32_e32 v136, v142, v154, vcc
	v_lshlrev_b32_e32 v172, 2, v136
	v_cmp_eq_u32_e32 vcc, 0, v144
	s_waitcnt lgkmcnt(0)
	v_add_f32_e32 v134, v134, v135
	ds_bpermute_b32 v135, v172, v134
	s_and_saveexec_b64 s[4:5], vcc
	s_cbranch_execz .LBB0_504
	s_waitcnt lgkmcnt(0)
	v_add_f32_e32 v134, v134, v135
	ds_write_b32 v173, v134
.LBB0_504:
	s_or_b64 exec, exec, s[4:5]
	v_or_b32_e32 v136, 16, v130
	v_ashrrev_i32_e32 v137, 31, v136
	s_waitcnt lgkmcnt(0)
	v_lshlrev_b64 v[134:135], 12, v[136:137]
	v_lshl_add_u64 v[138:139], s[44:45], 0, v[134:135]
	v_lshl_add_u64 v[150:151], v[128:129], 2, v[138:139]
	s_nop 0
	s_waitcnt vmcnt(15)
	v_pk_add_f32 v[110:111], v[110:111], v[204:205]
	v_pk_add_f32 v[108:109], v[108:109], v[202:203]
	s_waitcnt vmcnt(14)
	v_pk_add_f32 v[106:107], v[106:107], v[208:209]
	v_pk_add_f32 v[104:105], v[104:105], v[206:207]
	s_waitcnt vmcnt(13)
	v_pk_add_f32 v[102:103], v[102:103], v[212:213]
	v_pk_add_f32 v[100:101], v[100:101], v[210:211]
	v_mul_f32_e32 v138, v109, v109
	v_mul_f32_e32 v139, v111, v111
	v_mul_f32_e32 v140, v105, v105
	v_mul_f32_e32 v141, v107, v107
	s_waitcnt vmcnt(12)
	v_pk_add_f32 v[98:99], v[98:99], v[216:217]
	v_pk_add_f32 v[96:97], v[96:97], v[214:215]
	v_add_u32_e32 v199, 0x90000, v198
	global_load_dwordx4 v[202:205], v199, s[44:45] nt
	global_load_dwordx4 v[206:209], v199, s[44:45] offset:64 nt
	global_load_dwordx4 v[210:213], v199, s[44:45] offset:512 nt
	global_load_dwordx4 v[214:217], v199, s[44:45] offset:576 nt
	v_mul_f32_e32 v142, v101, v101
	v_mul_f32_e32 v143, v103, v103
	v_fmac_f32_e32 v138, v108, v108
	v_fmac_f32_e32 v139, v110, v110
	v_fmac_f32_e32 v140, v104, v104
	v_fmac_f32_e32 v141, v106, v106
	v_mul_f32_e32 v144, v97, v97
	v_mul_f32_e32 v145, v99, v99
	v_fmac_f32_e32 v142, v100, v100
	v_fmac_f32_e32 v143, v102, v102
	v_add_f32_e32 v138, v138, v139
	v_add_f32_e32 v139, v140, v141
	v_fmac_f32_e32 v144, v96, v96
	v_fmac_f32_e32 v145, v98, v98
	v_add_f32_e32 v140, v142, v143
	v_add_f32_e32 v138, v138, v139
	v_add_f32_e32 v138, v138, v140
	v_add_f32_e32 v139, v144, v145
	v_add_f32_e32 v138, v138, v139
	ds_bpermute_b32 v139, v171, v138
	s_waitcnt lgkmcnt(0)
	v_add_f32_e32 v138, v138, v139
	ds_bpermute_b32 v139, v172, v138
	s_and_saveexec_b64 s[4:5], vcc
	s_cbranch_execz .LBB0_506
	s_waitcnt lgkmcnt(0)
	v_add_f32_e32 v138, v138, v139
	ds_write_b32 v173, v138 offset:64
.LBB0_506:
	s_or_b64 exec, exec, s[4:5]
	v_or_b32_e32 v140, 32, v130
	v_ashrrev_i32_e32 v141, 31, v140
	s_waitcnt lgkmcnt(0)
	v_lshlrev_b64 v[138:139], 12, v[140:141]
	v_lshl_add_u64 v[142:143], s[44:45], 0, v[138:139]
	v_lshl_add_u64 v[154:155], v[128:129], 2, v[142:143]
	s_nop 0
	s_waitcnt vmcnt(15)
	v_pk_add_f32 v[94:95], v[94:95], v[236:237]
	v_pk_add_f32 v[92:93], v[92:93], v[234:235]
	s_waitcnt vmcnt(14)
	v_pk_add_f32 v[90:91], v[90:91], v[240:241]
	v_pk_add_f32 v[88:89], v[88:89], v[238:239]
	s_waitcnt vmcnt(13)
	v_pk_add_f32 v[86:87], v[86:87], v[244:245]
	v_pk_add_f32 v[84:85], v[84:85], v[242:243]
	v_mul_f32_e32 v142, v93, v93
	v_mul_f32_e32 v143, v95, v95
	v_mul_f32_e32 v144, v89, v89
	v_mul_f32_e32 v145, v91, v91
	s_waitcnt vmcnt(12)
	v_pk_add_f32 v[82:83], v[82:83], v[248:249]
	v_pk_add_f32 v[80:81], v[80:81], v[246:247]
	v_add_u32_e32 v199, 0xa0000, v198
	global_load_dwordx4 v[234:237], v199, s[44:45] nt
	global_load_dwordx4 v[238:241], v199, s[44:45] offset:64 nt
	global_load_dwordx4 v[242:245], v199, s[44:45] offset:512 nt
	global_load_dwordx4 v[246:249], v199, s[44:45] offset:576 nt
	v_mul_f32_e32 v146, v85, v85
	v_mul_f32_e32 v147, v87, v87
	v_fmac_f32_e32 v142, v92, v92
	v_fmac_f32_e32 v143, v94, v94
	v_fmac_f32_e32 v144, v88, v88
	v_fmac_f32_e32 v145, v90, v90
	v_mul_f32_e32 v148, v81, v81
	v_mul_f32_e32 v149, v83, v83
	v_fmac_f32_e32 v146, v84, v84
	v_fmac_f32_e32 v147, v86, v86
	v_add_f32_e32 v142, v142, v143
	v_add_f32_e32 v143, v144, v145
	v_fmac_f32_e32 v148, v80, v80
	v_fmac_f32_e32 v149, v82, v82
	v_add_f32_e32 v144, v146, v147
	v_add_f32_e32 v142, v142, v143
	v_add_f32_e32 v142, v142, v144
	v_add_f32_e32 v143, v148, v149
	v_add_f32_e32 v142, v142, v143
	ds_bpermute_b32 v143, v171, v142
	s_waitcnt lgkmcnt(0)
	v_add_f32_e32 v142, v142, v143
	ds_bpermute_b32 v143, v172, v142
	s_and_saveexec_b64 s[4:5], vcc
	s_cbranch_execz .LBB0_508
	s_waitcnt lgkmcnt(0)
	v_add_f32_e32 v142, v142, v143
	ds_write_b32 v173, v142 offset:128
.LBB0_508:
	s_or_b64 exec, exec, s[4:5]
	v_or_b32_e32 v144, 48, v130
	v_ashrrev_i32_e32 v145, 31, v144
	s_waitcnt lgkmcnt(0)
	v_lshlrev_b64 v[142:143], 12, v[144:145]
	v_lshl_add_u64 v[146:147], s[44:45], 0, v[142:143]
	v_lshl_add_u64 v[158:159], v[128:129], 2, v[146:147]
	s_nop 0
	s_waitcnt vmcnt(15)
	v_pk_add_f32 v[78:79], v[78:79], v[220:221]
	v_pk_add_f32 v[146:147], v[76:77], v[218:219]
	s_waitcnt vmcnt(14)
	v_pk_add_f32 v[74:75], v[74:75], v[224:225]
	v_pk_add_f32 v[76:77], v[72:73], v[222:223]
	s_waitcnt vmcnt(13)
	v_pk_add_f32 v[70:71], v[70:71], v[228:229]
	v_pk_add_f32 v[68:69], v[68:69], v[226:227]
	v_mul_f32_e32 v72, v147, v147
	v_mul_f32_e32 v73, v79, v79
	v_mul_f32_e32 v148, v77, v77
	v_mul_f32_e32 v149, v75, v75
	s_waitcnt vmcnt(12)
	v_pk_add_f32 v[66:67], v[66:67], v[252:253]
	v_pk_add_f32 v[64:65], v[64:65], v[250:251]
	v_add_u32_e32 v199, 0xb0000, v198
	global_load_dwordx4 v[218:221], v199, s[44:45] nt
	global_load_dwordx4 v[222:225], v199, s[44:45] offset:64 nt
	global_load_dwordx4 v[226:229], v199, s[44:45] offset:512 nt
	global_load_dwordx4 v[250:253], v199, s[44:45] offset:576 nt
	v_mul_f32_e32 v150, v69, v69
	v_mul_f32_e32 v151, v71, v71
	v_fmac_f32_e32 v72, v146, v146
	v_fmac_f32_e32 v73, v78, v78
	v_fmac_f32_e32 v148, v76, v76
	v_fmac_f32_e32 v149, v74, v74
	v_mul_f32_e32 v152, v65, v65
	v_mul_f32_e32 v153, v67, v67
	v_fmac_f32_e32 v150, v68, v68
	v_fmac_f32_e32 v151, v70, v70
	v_add_f32_e32 v72, v72, v73
	v_add_f32_e32 v73, v148, v149
	v_fmac_f32_e32 v152, v64, v64
	v_fmac_f32_e32 v153, v66, v66
	v_add_f32_e32 v148, v150, v151
	v_add_f32_e32 v72, v72, v73
	v_add_f32_e32 v72, v72, v148
	v_add_f32_e32 v73, v152, v153
	v_add_f32_e32 v72, v72, v73
	ds_bpermute_b32 v73, v171, v72
	s_waitcnt lgkmcnt(0)
	v_add_f32_e32 v72, v72, v73
	ds_bpermute_b32 v73, v172, v72
	s_and_saveexec_b64 s[4:5], vcc
	s_cbranch_execz .LBB0_510
	s_waitcnt lgkmcnt(0)
	v_add_f32_e32 v72, v72, v73
	ds_write_b32 v173, v72 offset:192
.LBB0_510:
	s_or_b64 exec, exec, s[4:5]
	s_mov_b64 s[4:5], 0x80000
	s_waitcnt lgkmcnt(0)
	v_lshl_add_u64 v[72:73], v[132:133], 0, s[4:5]
	v_lshl_add_u64 v[148:149], s[44:45], 0, v[72:73]
	v_lshl_add_u64 v[160:161], v[128:129], 2, v[148:149]
	s_nop 0
	s_waitcnt vmcnt(15)
	v_pk_add_f32 v[62:63], v[62:63], v[184:185]
	v_pk_add_f32 v[148:149], v[60:61], v[182:183]
	s_waitcnt vmcnt(14)
	v_pk_add_f32 v[58:59], v[58:59], v[188:189]
	v_pk_add_f32 v[60:61], v[56:57], v[186:187]
	s_waitcnt vmcnt(13)
	v_pk_add_f32 v[54:55], v[54:55], v[192:193]
	v_pk_add_f32 v[52:53], v[52:53], v[190:191]
	v_mul_f32_e32 v56, v149, v149
	v_mul_f32_e32 v57, v63, v63
	v_mul_f32_e32 v150, v61, v61
	v_mul_f32_e32 v151, v59, v59
	s_waitcnt vmcnt(12)
	v_pk_add_f32 v[50:51], v[50:51], v[196:197]
	v_pk_add_f32 v[48:49], v[48:49], v[194:195]
	v_mul_f32_e32 v152, v53, v53
	v_mul_f32_e32 v153, v55, v55
	v_fmac_f32_e32 v56, v148, v148
	v_fmac_f32_e32 v57, v62, v62
	v_fmac_f32_e32 v150, v60, v60
	v_fmac_f32_e32 v151, v58, v58
	v_mul_f32_e32 v154, v49, v49
	v_mul_f32_e32 v155, v51, v51
	v_fmac_f32_e32 v152, v52, v52
	v_fmac_f32_e32 v153, v54, v54
	v_add_f32_e32 v56, v56, v57
	v_add_f32_e32 v57, v150, v151
	v_fmac_f32_e32 v154, v48, v48
	v_fmac_f32_e32 v155, v50, v50
	v_add_f32_e32 v150, v152, v153
	v_add_f32_e32 v56, v56, v57
	v_add_f32_e32 v56, v56, v150
	v_add_f32_e32 v57, v154, v155
	v_add_f32_e32 v56, v56, v57
	ds_bpermute_b32 v57, v171, v56
	s_waitcnt lgkmcnt(0)
	v_add_f32_e32 v56, v56, v57
	ds_bpermute_b32 v57, v172, v56
	s_and_saveexec_b64 s[4:5], vcc
	s_cbranch_execz .LBB0_512
	s_waitcnt lgkmcnt(0)
	v_add_f32_e32 v56, v56, v57
	ds_write_b32 v173, v56 offset:512
.LBB0_512:
	s_or_b64 exec, exec, s[4:5]
	s_mov_b64 s[4:5], 0x90000
	s_waitcnt lgkmcnt(0)
	v_lshl_add_u64 v[56:57], v[132:133], 0, s[4:5]
	v_lshl_add_u64 v[150:151], s[44:45], 0, v[56:57]
	v_lshl_add_u64 v[162:163], v[128:129], 2, v[150:151]
	s_nop 0
	s_waitcnt vmcnt(11)
	v_pk_add_f32 v[46:47], v[46:47], v[204:205]
	v_pk_add_f32 v[150:151], v[44:45], v[202:203]
	s_waitcnt vmcnt(10)
	v_pk_add_f32 v[42:43], v[42:43], v[208:209]
	v_pk_add_f32 v[44:45], v[40:41], v[206:207]
	s_waitcnt vmcnt(9)
	v_pk_add_f32 v[38:39], v[38:39], v[212:213]
	v_pk_add_f32 v[36:37], v[36:37], v[210:211]
	v_mul_f32_e32 v40, v151, v151
	v_mul_f32_e32 v41, v47, v47
	v_mul_f32_e32 v152, v45, v45
	v_mul_f32_e32 v153, v43, v43
	s_waitcnt vmcnt(8)
	v_pk_add_f32 v[34:35], v[34:35], v[216:217]
	v_pk_add_f32 v[32:33], v[32:33], v[214:215]
	v_mul_f32_e32 v154, v37, v37
	v_mul_f32_e32 v155, v39, v39
	v_fmac_f32_e32 v40, v150, v150
	v_fmac_f32_e32 v41, v46, v46
	v_fmac_f32_e32 v152, v44, v44
	v_fmac_f32_e32 v153, v42, v42
	v_mul_f32_e32 v156, v33, v33
	v_mul_f32_e32 v157, v35, v35
	v_fmac_f32_e32 v154, v36, v36
	v_fmac_f32_e32 v155, v38, v38
	v_add_f32_e32 v40, v40, v41
	v_add_f32_e32 v41, v152, v153
	v_fmac_f32_e32 v156, v32, v32
	v_fmac_f32_e32 v157, v34, v34
	v_add_f32_e32 v152, v154, v155
	v_add_f32_e32 v40, v40, v41
	v_add_f32_e32 v40, v40, v152
	v_add_f32_e32 v41, v156, v157
	v_add_f32_e32 v40, v40, v41
	ds_bpermute_b32 v41, v171, v40
	s_waitcnt lgkmcnt(0)
	v_add_f32_e32 v40, v40, v41
	ds_bpermute_b32 v41, v172, v40
	s_and_saveexec_b64 s[4:5], vcc
	s_cbranch_execz .LBB0_514
	s_waitcnt lgkmcnt(0)
	v_add_f32_e32 v40, v40, v41
	ds_write_b32 v173, v40 offset:576
.LBB0_514:
	s_or_b64 exec, exec, s[4:5]
	s_mov_b64 s[4:5], 0xa0000
	s_waitcnt lgkmcnt(0)
	v_lshl_add_u64 v[40:41], v[132:133], 0, s[4:5]
	v_lshl_add_u64 v[152:153], s[44:45], 0, v[40:41]
	v_lshl_add_u64 v[164:165], v[128:129], 2, v[152:153]
	s_nop 0
	s_waitcnt vmcnt(7)
	v_pk_add_f32 v[30:31], v[30:31], v[236:237]
	v_pk_add_f32 v[152:153], v[28:29], v[234:235]
	s_waitcnt vmcnt(6)
	v_pk_add_f32 v[26:27], v[26:27], v[240:241]
	v_pk_add_f32 v[28:29], v[24:25], v[238:239]
	s_waitcnt vmcnt(5)
	v_pk_add_f32 v[22:23], v[22:23], v[244:245]
	v_pk_add_f32 v[20:21], v[20:21], v[242:243]
	v_mul_f32_e32 v24, v153, v153
	v_mul_f32_e32 v25, v31, v31
	v_mul_f32_e32 v154, v29, v29
	v_mul_f32_e32 v155, v27, v27
	s_waitcnt vmcnt(4)
	v_pk_add_f32 v[18:19], v[18:19], v[248:249]
	v_pk_add_f32 v[16:17], v[16:17], v[246:247]
	v_mul_f32_e32 v156, v21, v21
	v_mul_f32_e32 v157, v23, v23
	v_fmac_f32_e32 v24, v152, v152
	v_fmac_f32_e32 v25, v30, v30
	v_fmac_f32_e32 v154, v28, v28
	v_fmac_f32_e32 v155, v26, v26
	v_mul_f32_e32 v158, v17, v17
	v_mul_f32_e32 v159, v19, v19
	v_fmac_f32_e32 v156, v20, v20
	v_fmac_f32_e32 v157, v22, v22
	v_add_f32_e32 v24, v24, v25
	v_add_f32_e32 v25, v154, v155
	v_fmac_f32_e32 v158, v16, v16
	v_fmac_f32_e32 v159, v18, v18
	v_add_f32_e32 v154, v156, v157
	v_add_f32_e32 v24, v24, v25
	v_add_f32_e32 v24, v24, v154
	v_add_f32_e32 v25, v158, v159
	v_add_f32_e32 v24, v24, v25
	ds_bpermute_b32 v25, v171, v24
	s_waitcnt lgkmcnt(0)
	v_add_f32_e32 v24, v24, v25
	ds_bpermute_b32 v25, v172, v24
	s_and_saveexec_b64 s[4:5], vcc
	s_cbranch_execz .LBB0_516
	s_waitcnt lgkmcnt(0)
	v_add_f32_e32 v24, v24, v25
	ds_write_b32 v173, v24 offset:640
.LBB0_516:
	s_or_b64 exec, exec, s[4:5]
	s_mov_b64 s[4:5], 0xb0000
	s_waitcnt lgkmcnt(0)
	v_lshl_add_u64 v[24:25], v[132:133], 0, s[4:5]
	v_lshl_add_u64 v[154:155], s[44:45], 0, v[24:25]
	v_lshl_add_u64 v[162:163], v[128:129], 2, v[154:155]
	s_waitcnt vmcnt(3)
	v_pk_add_f32 v[166:167], v[14:15], v[220:221]
	v_pk_add_f32 v[168:169], v[12:13], v[218:219]
	s_waitcnt vmcnt(2)
	v_pk_add_f32 v[162:163], v[10:11], v[224:225]
	v_pk_add_f32 v[164:165], v[8:9], v[222:223]
	s_waitcnt vmcnt(1)
	v_pk_add_f32 v[158:159], v[6:7], v[228:229]
	v_pk_add_f32 v[160:161], v[4:5], v[226:227]
	s_waitcnt vmcnt(0)
	v_pk_add_f32 v[154:155], v[2:3], v[252:253]
	v_pk_add_f32 v[156:157], v[0:1], v[250:251]
	v_mul_f32_e32 v0, v169, v169
	v_mul_f32_e32 v1, v167, v167
	v_mul_f32_e32 v2, v165, v165
	v_mul_f32_e32 v3, v163, v163
	v_mul_f32_e32 v4, v161, v161
	v_mul_f32_e32 v5, v159, v159
	v_fmac_f32_e32 v0, v168, v168
	v_fmac_f32_e32 v1, v166, v166
	v_fmac_f32_e32 v2, v164, v164
	v_fmac_f32_e32 v3, v162, v162
	v_mul_f32_e32 v6, v157, v157
	v_mul_f32_e32 v7, v155, v155
	v_fmac_f32_e32 v4, v160, v160
	v_fmac_f32_e32 v5, v158, v158
	v_add_f32_e32 v0, v0, v1
	v_add_f32_e32 v1, v2, v3
	v_fmac_f32_e32 v6, v156, v156
	v_fmac_f32_e32 v7, v154, v154
	v_add_f32_e32 v2, v4, v5
	v_add_f32_e32 v0, v0, v1
	v_add_f32_e32 v0, v0, v2
	v_add_f32_e32 v1, v6, v7
	v_add_f32_e32 v0, v0, v1
	ds_bpermute_b32 v1, v171, v0
	s_waitcnt lgkmcnt(0)
	v_add_f32_e32 v0, v0, v1
	ds_bpermute_b32 v1, v172, v0
	s_and_saveexec_b64 s[4:5], vcc
	s_cbranch_execz .LBB0_518
	s_waitcnt lgkmcnt(0)
	v_add_f32_e32 v0, v0, v1
	ds_write_b32 v173, v0 offset:704

.LBB0_530:
	v_lshl_add_u64 v[130:131], v[130:131], 2, s[10:11]
	global_load_dword v182, v[130:131], off sc1
	global_load_dword v183, v[130:131], off offset:64 sc1
	global_load_dword v184, v[130:131], off offset:128 sc1
	global_load_dword v185, v[130:131], off offset:192 sc1
	global_load_dword v186, v[130:131], off offset:512 sc1
	global_load_dword v187, v[130:131], off offset:576 sc1
	global_load_dword v188, v[130:131], off offset:640 sc1
	global_load_dword v189, v[130:131], off offset:704 sc1
	v_mov_b32_e32 v178, 0x3727c5ac
	v_lshl_add_u64 v[132:133], s[66:67], 0, v[132:133]
	v_lshlrev_b64 v[128:129], 2, v[128:129]
	v_lshl_add_u64 v[132:133], v[132:133], 0, v[128:129]
	v_lshl_add_u64 v[136:137], v[136:137], 2, s[10:11]
	s_waitcnt vmcnt(0)
	v_mov_b32_e32 v170, v182
	v_fmamk_f32 v170, v170, 0x3a800000, v178
	v_rsq_f32_e32 v170, v170
	s_nop 0
	v_pk_mul_f32 v[124:125], v[124:125], v[170:171] op_sel_hi:[1,0]
	v_pk_mul_f32 v[126:127], v[126:127], v[170:171] op_sel_hi:[1,0]
	v_pk_mul_f32 v[120:121], v[120:121], v[170:171] op_sel_hi:[1,0]
	v_pk_mul_f32 v[122:123], v[122:123], v[170:171] op_sel_hi:[1,0]
	v_pk_mul_f32 v[172:173], v[116:117], v[170:171] op_sel_hi:[1,0]
	v_pk_mul_f32 v[174:175], v[118:119], v[170:171] op_sel_hi:[1,0]
	v_pk_mul_f32 v[176:177], v[112:113], v[170:171] op_sel_hi:[1,0]
	v_pk_mul_f32 v[170:171], v[114:115], v[170:171] op_sel_hi:[1,0]
	v_pk_mul_f32 v[114:115], v[14:15], v[126:127]
	v_pk_mul_f32 v[112:113], v[12:13], v[124:125]
	v_pk_mul_f32 v[118:119], v[10:11], v[122:123]
	v_pk_mul_f32 v[116:117], v[8:9], v[120:121]
	v_pk_mul_f32 v[122:123], v[6:7], v[174:175]
	v_pk_mul_f32 v[120:121], v[4:5], v[172:173]
	v_pk_mul_f32 v[126:127], v[2:3], v[170:171]
	v_pk_mul_f32 v[124:125], v[0:1], v[176:177]
	global_store_dwordx4 v[132:133], v[112:115], off nt
	global_store_dwordx4 v[132:133], v[116:119], off offset:64 nt
	global_store_dwordx4 v[132:133], v[120:123], off offset:512 nt
	global_store_dwordx4 v[132:133], v[124:127], off offset:576 nt
	v_mov_b32_e32 v112, v183
	v_lshl_add_u64 v[114:115], s[66:67], 0, v[134:135]
	v_lshl_add_u64 v[114:115], v[114:115], 0, v[128:129]
	v_lshl_add_u64 v[116:117], v[140:141], 2, s[10:11]
	v_fmamk_f32 v112, v112, 0x3a800000, v178
	v_rsq_f32_e32 v112, v112
	s_nop 0
	v_pk_mul_f32 v[108:109], v[108:109], v[112:113] op_sel_hi:[1,0]
	v_pk_mul_f32 v[110:111], v[110:111], v[112:113] op_sel_hi:[1,0]
	v_pk_mul_f32 v[104:105], v[104:105], v[112:113] op_sel_hi:[1,0]
	v_pk_mul_f32 v[106:107], v[106:107], v[112:113] op_sel_hi:[1,0]
	v_pk_mul_f32 v[118:119], v[100:101], v[112:113] op_sel_hi:[1,0]
	v_pk_mul_f32 v[120:121], v[102:103], v[112:113] op_sel_hi:[1,0]
	v_pk_mul_f32 v[122:123], v[96:97], v[112:113] op_sel_hi:[1,0]
	v_pk_mul_f32 v[112:113], v[98:99], v[112:113] op_sel_hi:[1,0]
	v_pk_mul_f32 v[98:99], v[14:15], v[110:111]
	v_pk_mul_f32 v[96:97], v[12:13], v[108:109]
	v_pk_mul_f32 v[102:103], v[10:11], v[106:107]
	v_pk_mul_f32 v[100:101], v[8:9], v[104:105]
	v_pk_mul_f32 v[106:107], v[6:7], v[120:121]
	v_pk_mul_f32 v[104:105], v[4:5], v[118:119]
	v_pk_mul_f32 v[110:111], v[2:3], v[112:113]
	v_pk_mul_f32 v[108:109], v[0:1], v[122:123]
	global_store_dwordx4 v[114:115], v[96:99], off nt
	global_store_dwordx4 v[114:115], v[100:103], off offset:64 nt
	global_store_dwordx4 v[114:115], v[104:107], off offset:512 nt
	global_store_dwordx4 v[114:115], v[108:111], off offset:576 nt
	v_mov_b32_e32 v96, v184
	v_lshl_add_u64 v[98:99], s[66:67], 0, v[138:139]
	v_lshl_add_u64 v[98:99], v[98:99], 0, v[128:129]
	v_lshl_add_u64 v[100:101], v[144:145], 2, s[10:11]
	v_fmamk_f32 v96, v96, 0x3a800000, v178
	v_rsq_f32_e32 v96, v96
	s_nop 0
	v_pk_mul_f32 v[92:93], v[92:93], v[96:97] op_sel_hi:[1,0]
	v_pk_mul_f32 v[94:95], v[94:95], v[96:97] op_sel_hi:[1,0]
	v_pk_mul_f32 v[88:89], v[88:89], v[96:97] op_sel_hi:[1,0]
	v_pk_mul_f32 v[90:91], v[90:91], v[96:97] op_sel_hi:[1,0]
	v_pk_mul_f32 v[102:103], v[84:85], v[96:97] op_sel_hi:[1,0]
	v_pk_mul_f32 v[104:105], v[86:87], v[96:97] op_sel_hi:[1,0]
	v_pk_mul_f32 v[106:107], v[80:81], v[96:97] op_sel_hi:[1,0]
	v_pk_mul_f32 v[96:97], v[82:83], v[96:97] op_sel_hi:[1,0]
	v_pk_mul_f32 v[82:83], v[14:15], v[94:95]
	v_pk_mul_f32 v[80:81], v[12:13], v[92:93]
	v_pk_mul_f32 v[86:87], v[10:11], v[90:91]
	v_pk_mul_f32 v[84:85], v[8:9], v[88:89]
	v_pk_mul_f32 v[90:91], v[6:7], v[104:105]
	v_pk_mul_f32 v[88:89], v[4:5], v[102:103]
	v_pk_mul_f32 v[94:95], v[2:3], v[96:97]
	v_pk_mul_f32 v[92:93], v[0:1], v[106:107]
	global_store_dwordx4 v[98:99], v[80:83], off nt
	global_store_dwordx4 v[98:99], v[84:87], off offset:64 nt
	global_store_dwordx4 v[98:99], v[88:91], off offset:512 nt
	global_store_dwordx4 v[98:99], v[92:95], off offset:576 nt
	v_mov_b32_e32 v80, v185
	v_lshl_add_u64 v[82:83], s[66:67], 0, v[142:143]
	v_lshl_add_u64 v[82:83], v[82:83], 0, v[128:129]
	v_fmamk_f32 v80, v80, 0x3a800000, v178
	v_rsq_f32_e32 v80, v80
	s_nop 0
	v_pk_mul_f32 v[84:85], v[146:147], v[80:81] op_sel_hi:[1,0]
	v_pk_mul_f32 v[78:79], v[78:79], v[80:81] op_sel_hi:[1,0]
	v_pk_mul_f32 v[76:77], v[76:77], v[80:81] op_sel_hi:[1,0]
	v_pk_mul_f32 v[74:75], v[74:75], v[80:81] op_sel_hi:[1,0]
	v_pk_mul_f32 v[86:87], v[68:69], v[80:81] op_sel_hi:[1,0]
	v_pk_mul_f32 v[88:89], v[70:71], v[80:81] op_sel_hi:[1,0]
	v_pk_mul_f32 v[90:91], v[64:65], v[80:81] op_sel_hi:[1,0]
	v_pk_mul_f32 v[80:81], v[66:67], v[80:81] op_sel_hi:[1,0]
	v_pk_mul_f32 v[66:67], v[14:15], v[78:79]
	v_pk_mul_f32 v[64:65], v[12:13], v[84:85]
	v_pk_mul_f32 v[70:71], v[10:11], v[74:75]
	v_pk_mul_f32 v[68:69], v[8:9], v[76:77]
	v_pk_mul_f32 v[76:77], v[6:7], v[88:89]
	v_pk_mul_f32 v[74:75], v[4:5], v[86:87]
	v_pk_mul_f32 v[80:81], v[2:3], v[80:81]
	v_pk_mul_f32 v[78:79], v[0:1], v[90:91]
	global_store_dwordx4 v[82:83], v[64:67], off nt
	global_store_dwordx4 v[82:83], v[68:71], off offset:64 nt
	global_store_dwordx4 v[82:83], v[74:77], off offset:512 nt
	global_store_dwordx4 v[82:83], v[78:81], off offset:576 nt
	v_mov_b32_e32 v64, v186
	v_lshl_add_u64 v[66:67], s[66:67], 0, v[72:73]
	v_lshl_add_u64 v[66:67], v[66:67], 0, v[128:129]
	v_fmamk_f32 v64, v64, 0x3a800000, v178
	v_rsq_f32_e32 v64, v64
	s_nop 0
	v_pk_mul_f32 v[68:69], v[148:149], v[64:65] op_sel_hi:[1,0]
	v_pk_mul_f32 v[62:63], v[62:63], v[64:65] op_sel_hi:[1,0]
	v_pk_mul_f32 v[60:61], v[60:61], v[64:65] op_sel_hi:[1,0]
	v_pk_mul_f32 v[58:59], v[58:59], v[64:65] op_sel_hi:[1,0]
	v_pk_mul_f32 v[70:71], v[52:53], v[64:65] op_sel_hi:[1,0]
	v_pk_mul_f32 v[72:73], v[54:55], v[64:65] op_sel_hi:[1,0]
	v_pk_mul_f32 v[74:75], v[48:49], v[64:65] op_sel_hi:[1,0]
	v_pk_mul_f32 v[64:65], v[50:51], v[64:65] op_sel_hi:[1,0]
	v_pk_mul_f32 v[50:51], v[14:15], v[62:63]
	v_pk_mul_f32 v[48:49], v[12:13], v[68:69]
	v_pk_mul_f32 v[54:55], v[10:11], v[58:59]
	v_pk_mul_f32 v[52:53], v[8:9], v[60:61]
	v_pk_mul_f32 v[60:61], v[6:7], v[72:73]
	v_pk_mul_f32 v[58:59], v[4:5], v[70:71]
	v_pk_mul_f32 v[64:65], v[2:3], v[64:65]
	v_pk_mul_f32 v[62:63], v[0:1], v[74:75]
	global_store_dwordx4 v[66:67], v[48:51], off nt
	global_store_dwordx4 v[66:67], v[52:55], off offset:64 nt
	global_store_dwordx4 v[66:67], v[58:61], off offset:512 nt
	global_store_dwordx4 v[66:67], v[62:65], off offset:576 nt
	v_mov_b32_e32 v48, v187
	v_lshl_add_u64 v[50:51], s[66:67], 0, v[56:57]
	v_lshl_add_u64 v[50:51], v[50:51], 0, v[128:129]
	v_fmamk_f32 v48, v48, 0x3a800000, v178
	v_rsq_f32_e32 v48, v48
	s_nop 0
	v_pk_mul_f32 v[52:53], v[150:151], v[48:49] op_sel_hi:[1,0]
	v_pk_mul_f32 v[46:47], v[46:47], v[48:49] op_sel_hi:[1,0]
	v_pk_mul_f32 v[44:45], v[44:45], v[48:49] op_sel_hi:[1,0]
	v_pk_mul_f32 v[42:43], v[42:43], v[48:49] op_sel_hi:[1,0]
	v_pk_mul_f32 v[54:55], v[36:37], v[48:49] op_sel_hi:[1,0]
	v_pk_mul_f32 v[56:57], v[38:39], v[48:49] op_sel_hi:[1,0]
	v_pk_mul_f32 v[58:59], v[32:33], v[48:49] op_sel_hi:[1,0]
	v_pk_mul_f32 v[48:49], v[34:35], v[48:49] op_sel_hi:[1,0]
	v_pk_mul_f32 v[34:35], v[14:15], v[46:47]
	v_pk_mul_f32 v[32:33], v[12:13], v[52:53]
	v_pk_mul_f32 v[38:39], v[10:11], v[42:43]
	v_pk_mul_f32 v[36:37], v[8:9], v[44:45]
	v_pk_mul_f32 v[44:45], v[6:7], v[56:57]
	v_pk_mul_f32 v[42:43], v[4:5], v[54:55]
	v_pk_mul_f32 v[48:49], v[2:3], v[48:49]
	v_pk_mul_f32 v[46:47], v[0:1], v[58:59]
	global_store_dwordx4 v[50:51], v[32:35], off nt
	global_store_dwordx4 v[50:51], v[36:39], off offset:64 nt
	global_store_dwordx4 v[50:51], v[42:45], off offset:512 nt
	global_store_dwordx4 v[50:51], v[46:49], off offset:576 nt
	v_mov_b32_e32 v32, v188
	v_lshl_add_u64 v[34:35], s[66:67], 0, v[40:41]
	v_lshl_add_u64 v[34:35], v[34:35], 0, v[128:129]
	v_fmamk_f32 v32, v32, 0x3a800000, v178
	v_rsq_f32_e32 v32, v32
	s_nop 0
	v_pk_mul_f32 v[36:37], v[152:153], v[32:33] op_sel_hi:[1,0]
	v_pk_mul_f32 v[30:31], v[30:31], v[32:33] op_sel_hi:[1,0]
	v_pk_mul_f32 v[28:29], v[28:29], v[32:33] op_sel_hi:[1,0]
	v_pk_mul_f32 v[26:27], v[26:27], v[32:33] op_sel_hi:[1,0]
	v_pk_mul_f32 v[38:39], v[20:21], v[32:33] op_sel_hi:[1,0]
	v_pk_mul_f32 v[40:41], v[22:23], v[32:33] op_sel_hi:[1,0]
	v_pk_mul_f32 v[42:43], v[16:17], v[32:33] op_sel_hi:[1,0]
	v_pk_mul_f32 v[32:33], v[18:19], v[32:33] op_sel_hi:[1,0]
	v_pk_mul_f32 v[18:19], v[14:15], v[30:31]
	v_pk_mul_f32 v[16:17], v[12:13], v[36:37]
	v_pk_mul_f32 v[22:23], v[10:11], v[26:27]
	v_pk_mul_f32 v[20:21], v[8:9], v[28:29]
	v_pk_mul_f32 v[28:29], v[6:7], v[40:41]
	v_pk_mul_f32 v[26:27], v[4:5], v[38:39]
	v_pk_mul_f32 v[32:33], v[2:3], v[32:33]
	v_pk_mul_f32 v[30:31], v[0:1], v[42:43]
	global_store_dwordx4 v[34:35], v[16:19], off nt
	global_store_dwordx4 v[34:35], v[20:23], off offset:64 nt
	global_store_dwordx4 v[34:35], v[26:29], off offset:512 nt
	global_store_dwordx4 v[34:35], v[30:33], off offset:576 nt
	v_mov_b32_e32 v16, v189
	v_lshl_add_u64 v[18:19], s[66:67], 0, v[24:25]
	v_lshl_add_u64 v[18:19], v[18:19], 0, v[128:129]
	v_fmac_f32_e32 v178, 0x3a800000, v16
	v_rsq_f32_e32 v16, v178
	s_nop 0
	v_pk_mul_f32 v[20:21], v[168:169], v[16:17] op_sel_hi:[1,0]
	v_pk_mul_f32 v[22:23], v[166:167], v[16:17] op_sel_hi:[1,0]
	v_pk_mul_f32 v[24:25], v[164:165], v[16:17] op_sel_hi:[1,0]
	v_pk_mul_f32 v[26:27], v[162:163], v[16:17] op_sel_hi:[1,0]
	v_pk_mul_f32 v[28:29], v[160:161], v[16:17] op_sel_hi:[1,0]
	v_pk_mul_f32 v[30:31], v[158:159], v[16:17] op_sel_hi:[1,0]
	v_pk_mul_f32 v[32:33], v[156:157], v[16:17] op_sel_hi:[1,0]
	v_pk_mul_f32 v[16:17], v[154:155], v[16:17] op_sel_hi:[1,0]
	v_pk_mul_f32 v[14:15], v[14:15], v[22:23]
	v_pk_mul_f32 v[12:13], v[12:13], v[20:21]
	v_pk_mul_f32 v[10:11], v[10:11], v[26:27]
	v_pk_mul_f32 v[8:9], v[8:9], v[24:25]
	v_pk_mul_f32 v[6:7], v[6:7], v[30:31]
	v_pk_mul_f32 v[4:5], v[4:5], v[28:29]
	v_pk_mul_f32 v[2:3], v[2:3], v[16:17]
	v_pk_mul_f32 v[0:1], v[0:1], v[32:33]
	global_store_dwordx4 v[18:19], v[12:15], off nt
	global_store_dwordx4 v[18:19], v[8:11], off offset:64 nt
	global_store_dwordx4 v[18:19], v[4:7], off offset:512 nt
	global_store_dwordx4 v[18:19], v[0:3], off offset:576 nt

	.amdhsa_kernel _Z10fwd_kernel4Args
		.amdhsa_group_segment_fixed_size 0
		.amdhsa_private_segment_fixed_size 0
		.amdhsa_kernarg_size 368
		.amdhsa_user_sgpr_count 2
		.amdhsa_user_sgpr_dispatch_ptr 0
		.amdhsa_user_sgpr_queue_ptr 0
		.amdhsa_user_sgpr_kernarg_segment_ptr 1
		.amdhsa_user_sgpr_dispatch_id 0
		.amdhsa_user_sgpr_kernarg_preload_length 0
		.amdhsa_user_sgpr_kernarg_preload_offset 0
		.amdhsa_user_sgpr_private_segment_size 0
		.amdhsa_uses_dynamic_stack 0
		.amdhsa_enable_private_segment 0
		.amdhsa_system_sgpr_workgroup_id_x 1
		.amdhsa_system_sgpr_workgroup_id_y 0
		.amdhsa_system_sgpr_workgroup_id_z 0
		.amdhsa_system_sgpr_workgroup_info 0
		.amdhsa_system_vgpr_workitem_id 2
		.amdhsa_next_free_vgpr 256
		.amdhsa_next_free_sgpr 100
		.amdhsa_accum_offset 256
		.amdhsa_reserve_vcc 1
		.amdhsa_float_round_mode_32 0
		.amdhsa_float_round_mode_16_64 0
		.amdhsa_float_denorm_mode_32 3
		.amdhsa_float_denorm_mode_16_64 3
		.amdhsa_dx10_clamp 1
		.amdhsa_ieee_mode 1
		.amdhsa_fp16_overflow 0
		.amdhsa_tg_split 0
		.amdhsa_exception_fp_ieee_invalid_op 0
		.amdhsa_exception_fp_denorm_src 0
		.amdhsa_exception_fp_ieee_div_zero 0
		.amdhsa_exception_fp_ieee_overflow 0
		.amdhsa_exception_fp_ieee_underflow 0
		.amdhsa_exception_fp_ieee_inexact 0
		.amdhsa_exception_int_div_zero 0
	.end_amdhsa_kernel

amdhsa.kernels:
  - .agpr_count:     0
    .args:
      - .offset:         0
        .size:           112
        .value_kind:     by_value
      - .offset:         112
        .size:           4
        .value_kind:     hidden_block_count_x
      - .offset:         116
        .size:           4
        .value_kind:     hidden_block_count_y
      - .offset:         120
        .size:           4
        .value_kind:     hidden_block_count_z
      - .offset:         124
        .size:           2
        .value_kind:     hidden_group_size_x
      - .offset:         126
        .size:           2
        .value_kind:     hidden_group_size_y
      - .offset:         128
        .size:           2
        .value_kind:     hidden_group_size_z
      - .offset:         130
        .size:           2
        .value_kind:     hidden_remainder_x
      - .offset:         132
        .size:           2
        .value_kind:     hidden_remainder_y
      - .offset:         134
        .size:           2
        .value_kind:     hidden_remainder_z
      - .offset:         152
        .size:           8
        .value_kind:     hidden_global_offset_x
      - .offset:         160
        .size:           8
        .value_kind:     hidden_global_offset_y
      - .offset:         168
        .size:           8
        .value_kind:     hidden_global_offset_z
      - .offset:         176
        .size:           2
        .value_kind:     hidden_grid_dims
      - .offset:         200
        .size:           8
        .value_kind:     hidden_multigrid_sync_arg
      - .offset:         232
        .size:           4
        .value_kind:     hidden_dynamic_lds_size
    .group_segment_fixed_size: 0
    .kernarg_segment_align: 8
    .kernarg_segment_size: 368
    .language:       OpenCL C
    .language_version:
      - 2
      - 0
    .max_flat_workgroup_size: 512
    .name:           _Z10fwd_kernel4Args
    .private_segment_fixed_size: 0
    .sgpr_count:     106
    .sgpr_spill_count: 51
    .symbol:         _Z10fwd_kernel4Args.kd
    .uniform_work_group_size: 1
    .uses_dynamic_stack: false
    .vgpr_count:     256
    .vgpr_spill_count: 0
    .wavefront_size: 64
